# BM selected-attention: lazy running max - after the first list entry skip the max tree, exp directly and fall back to the exact max/rescale path (scores recomputed) only when a lane sum exceeds 256
# speedup vs baseline: 1.0138x; 1.0138x over previous
.Lbm2_nostag:
.Lbm2_blkA:
	s_lshl_b32 s12, s15, 12
	s_add_u32 s30, s46, s12
	s_addc_u32 s31, s47, 0
	global_load_dwordx4 v[20:23], v79, s[30:31]
	global_load_dwordx4 v[24:27], v79, s[30:31] offset:1024
	global_load_dwordx4 v[28:31], v79, s[30:31] offset:2048
	global_load_dwordx4 v[32:35], v79, s[30:31] offset:3072
	s_lshl_b32 s12, s15, 12
	s_add_u32 s30, s62, s12
	s_addc_u32 s31, s63, 0
	global_load_dwordx4 v[52:55], v79, s[30:31]
	global_load_dwordx4 v[56:59], v79, s[30:31] offset:1024
	global_load_dwordx4 v[60:63], v79, s[30:31] offset:2048
	global_load_dwordx4 v[64:67], v79, s[30:31] offset:3072
	s_add_i32 s14, s35, 2
	s_add_i32 s13, s25, -1
	s_min_i32 s14, s14, s13
	s_lshl_b32 s13, s14, 2
	s_add_i32 s13, s13, s96
	v_mov_b32_e32 v76, s13
	ds_read_b32 v76, v76 offset:16384
	s_cmp_ge_i32 s54, s21
	s_cselect_b32 s14, 1, 0
	s_bfe_u32 s29, s48, 0x40000
	s_cmp_eq_u32 s29, 0
	s_cbranch_scc1 .Lbm2_Ag0_skip
	s_waitcnt vmcnt(12)
	v_mfma_f32_16x16x32_fp8_fp8 v[84:87], v[2:3], v[164:165], 0
	v_mfma_f32_16x16x32_fp8_fp8 v[88:91], v[6:7], v[164:165], 0
	v_mfma_f32_16x16x32_fp8_fp8 v[92:95], v[12:13], v[164:165], 0
	v_mfma_f32_16x16x32_fp8_fp8 v[96:99], v[16:17], v[164:165], 0
	v_mfma_f32_16x16x32_fp8_fp8 v[84:87], v[4:5], v[166:167], v[84:87]
	v_mfma_f32_16x16x32_fp8_fp8 v[88:91], v[8:9], v[166:167], v[88:91]
	v_mfma_f32_16x16x32_fp8_fp8 v[92:95], v[14:15], v[166:167], v[92:95]
	v_mfma_f32_16x16x32_fp8_fp8 v[96:99], v[18:19], v[166:167], v[96:99]
	v_and_b32_e32 v199, s29, v244
	s_cmp_eq_u32 s14, 1
	v_cmp_ne_u32_e32 vcc, 0, v199
	s_cbranch_scc1 .Lbm2_Ag0_near
	v_add_f32_e32 v200, v81, v190
	v_cndmask_b32_e32 v200, v77, v200, vcc
	v_pk_fma_f32 v[84:85], v[84:85], s[16:17], v[200:201] op_sel_hi:[1,1,0]
	v_pk_fma_f32 v[86:87], v[86:87], s[16:17], v[200:201] op_sel_hi:[1,1,0]
	v_pk_fma_f32 v[88:89], v[88:89], s[16:17], v[200:201] op_sel_hi:[1,1,0]
	v_pk_fma_f32 v[90:91], v[90:91], s[16:17], v[200:201] op_sel_hi:[1,1,0]
	v_pk_fma_f32 v[92:93], v[92:93], s[16:17], v[200:201] op_sel_hi:[1,1,0]
	v_pk_fma_f32 v[94:95], v[94:95], s[16:17], v[200:201] op_sel_hi:[1,1,0]
	v_pk_fma_f32 v[96:97], v[96:97], s[16:17], v[200:201] op_sel_hi:[1,1,0]
	v_pk_fma_f32 v[98:99], v[98:99], s[16:17], v[200:201] op_sel_hi:[1,1,0]
	s_cmp_eq_u32 s35, 0
	s_cbranch_scc1 .Lbm2_Ag0_max
	v_exp_f32_e32 v84, v84
	v_exp_f32_e32 v85, v85
	v_exp_f32_e32 v86, v86
	v_exp_f32_e32 v87, v87
	v_exp_f32_e32 v88, v88
	v_exp_f32_e32 v89, v89
	v_exp_f32_e32 v90, v90
	v_exp_f32_e32 v91, v91
	v_exp_f32_e32 v92, v92
	v_exp_f32_e32 v93, v93
	v_exp_f32_e32 v94, v94
	v_exp_f32_e32 v95, v95
	v_exp_f32_e32 v96, v96
	v_exp_f32_e32 v97, v97
	v_exp_f32_e32 v98, v98
	v_exp_f32_e32 v99, v99
	v_pk_add_f32 v[248:249], v[84:85], v[86:87]
	v_pk_add_f32 v[248:249], v[248:249], v[88:89]
	v_pk_add_f32 v[248:249], v[248:249], v[90:91]
	v_pk_add_f32 v[248:249], v[248:249], v[92:93]
	v_pk_add_f32 v[248:249], v[248:249], v[94:95]
	v_pk_add_f32 v[248:249], v[248:249], v[96:97]
	v_pk_add_f32 v[248:249], v[248:249], v[98:99]
	v_add_f32_e32 v248, v248, v249
	v_cmp_lt_f32_e32 vcc, 0x43800000, v248
	s_cbranch_vccnz .Lbm2_Ag0_redo
	v_cvt_pk_fp8_f32 v84, v84, v85
	v_cvt_pk_fp8_f32 v85, v88, v89
	v_cvt_pk_fp8_f32 v84, v86, v87 op_sel:[0,0,1]
	v_cvt_pk_fp8_f32 v85, v90, v91 op_sel:[0,0,1]
	v_cvt_pk_fp8_f32 v86, v92, v93
	v_cvt_pk_fp8_f32 v87, v96, v97
	v_cvt_pk_fp8_f32 v86, v94, v95 op_sel:[0,0,1]
	v_cvt_pk_fp8_f32 v87, v98, v99 op_sel:[0,0,1]
	v_add_f32_e32 v194, v194, v248
	s_waitcnt vmcnt(8)
	s_nop 1
	v_mfma_f32_16x16x32_fp8_fp8 v[100:103], v[36:37], v[84:85], v[100:103]
	v_mfma_f32_16x16x32_fp8_fp8 v[104:107], v[38:39], v[84:85], v[104:107]
	v_mfma_f32_16x16x32_fp8_fp8 v[108:111], v[40:41], v[84:85], v[108:111]
	v_mfma_f32_16x16x32_fp8_fp8 v[112:115], v[42:43], v[84:85], v[112:115]
	v_mfma_f32_16x16x32_fp8_fp8 v[100:103], v[44:45], v[86:87], v[100:103]
	v_mfma_f32_16x16x32_fp8_fp8 v[104:107], v[46:47], v[86:87], v[104:107]
	v_mfma_f32_16x16x32_fp8_fp8 v[108:111], v[48:49], v[86:87], v[108:111]
	v_mfma_f32_16x16x32_fp8_fp8 v[112:115], v[50:51], v[86:87], v[112:115]
	s_branch .Lbm2_Ag0_skip
.Lbm2_Ag0_redo:
	v_mfma_f32_16x16x32_fp8_fp8 v[84:87], v[2:3], v[164:165], 0
	v_mfma_f32_16x16x32_fp8_fp8 v[88:91], v[6:7], v[164:165], 0
	v_mfma_f32_16x16x32_fp8_fp8 v[92:95], v[12:13], v[164:165], 0
	v_mfma_f32_16x16x32_fp8_fp8 v[96:99], v[16:17], v[164:165], 0
	v_mfma_f32_16x16x32_fp8_fp8 v[84:87], v[4:5], v[166:167], v[84:87]
	v_mfma_f32_16x16x32_fp8_fp8 v[88:91], v[8:9], v[166:167], v[88:91]
	v_mfma_f32_16x16x32_fp8_fp8 v[92:95], v[14:15], v[166:167], v[92:95]
	v_mfma_f32_16x16x32_fp8_fp8 v[96:99], v[18:19], v[166:167], v[96:99]
	s_nop 7
	v_pk_fma_f32 v[84:85], v[84:85], s[16:17], v[200:201] op_sel_hi:[1,1,0]
	v_pk_fma_f32 v[86:87], v[86:87], s[16:17], v[200:201] op_sel_hi:[1,1,0]
	v_pk_fma_f32 v[88:89], v[88:89], s[16:17], v[200:201] op_sel_hi:[1,1,0]
	v_pk_fma_f32 v[90:91], v[90:91], s[16:17], v[200:201] op_sel_hi:[1,1,0]
	v_pk_fma_f32 v[92:93], v[92:93], s[16:17], v[200:201] op_sel_hi:[1,1,0]
	v_pk_fma_f32 v[94:95], v[94:95], s[16:17], v[200:201] op_sel_hi:[1,1,0]
	v_pk_fma_f32 v[96:97], v[96:97], s[16:17], v[200:201] op_sel_hi:[1,1,0]
	v_pk_fma_f32 v[98:99], v[98:99], s[16:17], v[200:201] op_sel_hi:[1,1,0]

.Lbm2_Ag0_skip:
	s_bfe_u32 s29, s48, 0x40004
	s_cmp_eq_u32 s29, 0
	s_cbranch_scc1 .Lbm2_Ag1_skip
	s_waitcnt vmcnt(12)
	v_mfma_f32_16x16x32_fp8_fp8 v[84:87], v[2:3], v[168:169], 0
	v_mfma_f32_16x16x32_fp8_fp8 v[88:91], v[6:7], v[168:169], 0
	v_mfma_f32_16x16x32_fp8_fp8 v[92:95], v[12:13], v[168:169], 0
	v_mfma_f32_16x16x32_fp8_fp8 v[96:99], v[16:17], v[168:169], 0
	v_mfma_f32_16x16x32_fp8_fp8 v[84:87], v[4:5], v[170:171], v[84:87]
	v_mfma_f32_16x16x32_fp8_fp8 v[88:91], v[8:9], v[170:171], v[88:91]
	v_mfma_f32_16x16x32_fp8_fp8 v[92:95], v[14:15], v[170:171], v[92:95]
	v_mfma_f32_16x16x32_fp8_fp8 v[96:99], v[18:19], v[170:171], v[96:99]
	v_and_b32_e32 v199, s29, v244
	s_cmp_eq_u32 s14, 1
	v_cmp_ne_u32_e32 vcc, 0, v199
	s_cbranch_scc1 .Lbm2_Ag1_near
	v_add_f32_e32 v200, v81, v191
	v_cndmask_b32_e32 v200, v77, v200, vcc
	v_pk_fma_f32 v[84:85], v[84:85], s[16:17], v[200:201] op_sel_hi:[1,1,0]
	v_pk_fma_f32 v[86:87], v[86:87], s[16:17], v[200:201] op_sel_hi:[1,1,0]
	v_pk_fma_f32 v[88:89], v[88:89], s[16:17], v[200:201] op_sel_hi:[1,1,0]
	v_pk_fma_f32 v[90:91], v[90:91], s[16:17], v[200:201] op_sel_hi:[1,1,0]
	v_pk_fma_f32 v[92:93], v[92:93], s[16:17], v[200:201] op_sel_hi:[1,1,0]
	v_pk_fma_f32 v[94:95], v[94:95], s[16:17], v[200:201] op_sel_hi:[1,1,0]
	v_pk_fma_f32 v[96:97], v[96:97], s[16:17], v[200:201] op_sel_hi:[1,1,0]
	v_pk_fma_f32 v[98:99], v[98:99], s[16:17], v[200:201] op_sel_hi:[1,1,0]
	s_cmp_eq_u32 s35, 0
	s_cbranch_scc1 .Lbm2_Ag1_max
	v_exp_f32_e32 v84, v84
	v_exp_f32_e32 v85, v85
	v_exp_f32_e32 v86, v86
	v_exp_f32_e32 v87, v87
	v_exp_f32_e32 v88, v88
	v_exp_f32_e32 v89, v89
	v_exp_f32_e32 v90, v90
	v_exp_f32_e32 v91, v91
	v_exp_f32_e32 v92, v92
	v_exp_f32_e32 v93, v93
	v_exp_f32_e32 v94, v94
	v_exp_f32_e32 v95, v95
	v_exp_f32_e32 v96, v96
	v_exp_f32_e32 v97, v97
	v_exp_f32_e32 v98, v98
	v_exp_f32_e32 v99, v99
	v_pk_add_f32 v[248:249], v[84:85], v[86:87]
	v_pk_add_f32 v[248:249], v[248:249], v[88:89]
	v_pk_add_f32 v[248:249], v[248:249], v[90:91]
	v_pk_add_f32 v[248:249], v[248:249], v[92:93]
	v_pk_add_f32 v[248:249], v[248:249], v[94:95]
	v_pk_add_f32 v[248:249], v[248:249], v[96:97]
	v_pk_add_f32 v[248:249], v[248:249], v[98:99]
	v_add_f32_e32 v248, v248, v249
	v_cmp_lt_f32_e32 vcc, 0x43800000, v248
	s_cbranch_vccnz .Lbm2_Ag1_redo
	v_cvt_pk_fp8_f32 v84, v84, v85
	v_cvt_pk_fp8_f32 v85, v88, v89
	v_cvt_pk_fp8_f32 v84, v86, v87 op_sel:[0,0,1]
	v_cvt_pk_fp8_f32 v85, v90, v91 op_sel:[0,0,1]
	v_cvt_pk_fp8_f32 v86, v92, v93
	v_cvt_pk_fp8_f32 v87, v96, v97
	v_cvt_pk_fp8_f32 v86, v94, v95 op_sel:[0,0,1]
	v_cvt_pk_fp8_f32 v87, v98, v99 op_sel:[0,0,1]
	v_add_f32_e32 v195, v195, v248
	s_waitcnt vmcnt(8)
	s_nop 1
	v_mfma_f32_16x16x32_fp8_fp8 v[116:119], v[36:37], v[84:85], v[116:119]
	v_mfma_f32_16x16x32_fp8_fp8 v[120:123], v[38:39], v[84:85], v[120:123]
	v_mfma_f32_16x16x32_fp8_fp8 v[124:127], v[40:41], v[84:85], v[124:127]
	v_mfma_f32_16x16x32_fp8_fp8 v[128:131], v[42:43], v[84:85], v[128:131]
	v_mfma_f32_16x16x32_fp8_fp8 v[116:119], v[44:45], v[86:87], v[116:119]
	v_mfma_f32_16x16x32_fp8_fp8 v[120:123], v[46:47], v[86:87], v[120:123]
	v_mfma_f32_16x16x32_fp8_fp8 v[124:127], v[48:49], v[86:87], v[124:127]
	v_mfma_f32_16x16x32_fp8_fp8 v[128:131], v[50:51], v[86:87], v[128:131]
	s_branch .Lbm2_Ag1_skip
.Lbm2_Ag1_redo:
	v_mfma_f32_16x16x32_fp8_fp8 v[84:87], v[2:3], v[168:169], 0
	v_mfma_f32_16x16x32_fp8_fp8 v[88:91], v[6:7], v[168:169], 0
	v_mfma_f32_16x16x32_fp8_fp8 v[92:95], v[12:13], v[168:169], 0
	v_mfma_f32_16x16x32_fp8_fp8 v[96:99], v[16:17], v[168:169], 0
	v_mfma_f32_16x16x32_fp8_fp8 v[84:87], v[4:5], v[170:171], v[84:87]
	v_mfma_f32_16x16x32_fp8_fp8 v[88:91], v[8:9], v[170:171], v[88:91]
	v_mfma_f32_16x16x32_fp8_fp8 v[92:95], v[14:15], v[170:171], v[92:95]
	v_mfma_f32_16x16x32_fp8_fp8 v[96:99], v[18:19], v[170:171], v[96:99]
	s_nop 7
	v_pk_fma_f32 v[84:85], v[84:85], s[16:17], v[200:201] op_sel_hi:[1,1,0]
	v_pk_fma_f32 v[86:87], v[86:87], s[16:17], v[200:201] op_sel_hi:[1,1,0]
	v_pk_fma_f32 v[88:89], v[88:89], s[16:17], v[200:201] op_sel_hi:[1,1,0]
	v_pk_fma_f32 v[90:91], v[90:91], s[16:17], v[200:201] op_sel_hi:[1,1,0]
	v_pk_fma_f32 v[92:93], v[92:93], s[16:17], v[200:201] op_sel_hi:[1,1,0]
	v_pk_fma_f32 v[94:95], v[94:95], s[16:17], v[200:201] op_sel_hi:[1,1,0]
	v_pk_fma_f32 v[96:97], v[96:97], s[16:17], v[200:201] op_sel_hi:[1,1,0]
	v_pk_fma_f32 v[98:99], v[98:99], s[16:17], v[200:201] op_sel_hi:[1,1,0]

.Lbm2_Ag1_skip:
	s_bfe_u32 s29, s48, 0x40008
	s_cmp_eq_u32 s29, 0
	s_cbranch_scc1 .Lbm2_Ag2_skip
	s_waitcnt vmcnt(12)
	v_mfma_f32_16x16x32_fp8_fp8 v[84:87], v[2:3], v[182:183], 0
	v_mfma_f32_16x16x32_fp8_fp8 v[88:91], v[6:7], v[182:183], 0
	v_mfma_f32_16x16x32_fp8_fp8 v[92:95], v[12:13], v[182:183], 0
	v_mfma_f32_16x16x32_fp8_fp8 v[96:99], v[16:17], v[182:183], 0
	v_mfma_f32_16x16x32_fp8_fp8 v[84:87], v[4:5], v[184:185], v[84:87]
	v_mfma_f32_16x16x32_fp8_fp8 v[88:91], v[8:9], v[184:185], v[88:91]
	v_mfma_f32_16x16x32_fp8_fp8 v[92:95], v[14:15], v[184:185], v[92:95]
	v_mfma_f32_16x16x32_fp8_fp8 v[96:99], v[18:19], v[184:185], v[96:99]
	v_and_b32_e32 v199, s29, v244
	s_cmp_eq_u32 s14, 1
	v_cmp_ne_u32_e32 vcc, 0, v199
	s_cbranch_scc1 .Lbm2_Ag2_near
	v_add_f32_e32 v200, v81, v192
	v_cndmask_b32_e32 v200, v77, v200, vcc
	v_pk_fma_f32 v[84:85], v[84:85], s[16:17], v[200:201] op_sel_hi:[1,1,0]
	v_pk_fma_f32 v[86:87], v[86:87], s[16:17], v[200:201] op_sel_hi:[1,1,0]
	v_pk_fma_f32 v[88:89], v[88:89], s[16:17], v[200:201] op_sel_hi:[1,1,0]
	v_pk_fma_f32 v[90:91], v[90:91], s[16:17], v[200:201] op_sel_hi:[1,1,0]
	v_pk_fma_f32 v[92:93], v[92:93], s[16:17], v[200:201] op_sel_hi:[1,1,0]
	v_pk_fma_f32 v[94:95], v[94:95], s[16:17], v[200:201] op_sel_hi:[1,1,0]
	v_pk_fma_f32 v[96:97], v[96:97], s[16:17], v[200:201] op_sel_hi:[1,1,0]
	v_pk_fma_f32 v[98:99], v[98:99], s[16:17], v[200:201] op_sel_hi:[1,1,0]
	s_cmp_eq_u32 s35, 0
	s_cbranch_scc1 .Lbm2_Ag2_max
	v_exp_f32_e32 v84, v84
	v_exp_f32_e32 v85, v85
	v_exp_f32_e32 v86, v86
	v_exp_f32_e32 v87, v87
	v_exp_f32_e32 v88, v88
	v_exp_f32_e32 v89, v89
	v_exp_f32_e32 v90, v90
	v_exp_f32_e32 v91, v91
	v_exp_f32_e32 v92, v92
	v_exp_f32_e32 v93, v93
	v_exp_f32_e32 v94, v94
	v_exp_f32_e32 v95, v95
	v_exp_f32_e32 v96, v96
	v_exp_f32_e32 v97, v97
	v_exp_f32_e32 v98, v98
	v_exp_f32_e32 v99, v99
	v_pk_add_f32 v[248:249], v[84:85], v[86:87]
	v_pk_add_f32 v[248:249], v[248:249], v[88:89]
	v_pk_add_f32 v[248:249], v[248:249], v[90:91]
	v_pk_add_f32 v[248:249], v[248:249], v[92:93]
	v_pk_add_f32 v[248:249], v[248:249], v[94:95]
	v_pk_add_f32 v[248:249], v[248:249], v[96:97]
	v_pk_add_f32 v[248:249], v[248:249], v[98:99]
	v_add_f32_e32 v248, v248, v249
	v_cmp_lt_f32_e32 vcc, 0x43800000, v248
	s_cbranch_vccnz .Lbm2_Ag2_redo
	v_cvt_pk_fp8_f32 v84, v84, v85
	v_cvt_pk_fp8_f32 v85, v88, v89
	v_cvt_pk_fp8_f32 v84, v86, v87 op_sel:[0,0,1]
	v_cvt_pk_fp8_f32 v85, v90, v91 op_sel:[0,0,1]
	v_cvt_pk_fp8_f32 v86, v92, v93
	v_cvt_pk_fp8_f32 v87, v96, v97
	v_cvt_pk_fp8_f32 v86, v94, v95 op_sel:[0,0,1]
	v_cvt_pk_fp8_f32 v87, v98, v99 op_sel:[0,0,1]
	v_add_f32_e32 v196, v196, v248
	s_waitcnt vmcnt(8)
	s_nop 1
	v_mfma_f32_16x16x32_fp8_fp8 v[132:135], v[36:37], v[84:85], v[132:135]
	v_mfma_f32_16x16x32_fp8_fp8 v[136:139], v[38:39], v[84:85], v[136:139]
	v_mfma_f32_16x16x32_fp8_fp8 v[140:143], v[40:41], v[84:85], v[140:143]
	v_mfma_f32_16x16x32_fp8_fp8 v[144:147], v[42:43], v[84:85], v[144:147]
	v_mfma_f32_16x16x32_fp8_fp8 v[132:135], v[44:45], v[86:87], v[132:135]
	v_mfma_f32_16x16x32_fp8_fp8 v[136:139], v[46:47], v[86:87], v[136:139]
	v_mfma_f32_16x16x32_fp8_fp8 v[140:143], v[48:49], v[86:87], v[140:143]
	v_mfma_f32_16x16x32_fp8_fp8 v[144:147], v[50:51], v[86:87], v[144:147]
	s_branch .Lbm2_Ag2_skip
.Lbm2_Ag2_redo:
	v_mfma_f32_16x16x32_fp8_fp8 v[84:87], v[2:3], v[182:183], 0
	v_mfma_f32_16x16x32_fp8_fp8 v[88:91], v[6:7], v[182:183], 0
	v_mfma_f32_16x16x32_fp8_fp8 v[92:95], v[12:13], v[182:183], 0
	v_mfma_f32_16x16x32_fp8_fp8 v[96:99], v[16:17], v[182:183], 0
	v_mfma_f32_16x16x32_fp8_fp8 v[84:87], v[4:5], v[184:185], v[84:87]
	v_mfma_f32_16x16x32_fp8_fp8 v[88:91], v[8:9], v[184:185], v[88:91]
	v_mfma_f32_16x16x32_fp8_fp8 v[92:95], v[14:15], v[184:185], v[92:95]
	v_mfma_f32_16x16x32_fp8_fp8 v[96:99], v[18:19], v[184:185], v[96:99]
	s_nop 7
	v_pk_fma_f32 v[84:85], v[84:85], s[16:17], v[200:201] op_sel_hi:[1,1,0]
	v_pk_fma_f32 v[86:87], v[86:87], s[16:17], v[200:201] op_sel_hi:[1,1,0]
	v_pk_fma_f32 v[88:89], v[88:89], s[16:17], v[200:201] op_sel_hi:[1,1,0]
	v_pk_fma_f32 v[90:91], v[90:91], s[16:17], v[200:201] op_sel_hi:[1,1,0]
	v_pk_fma_f32 v[92:93], v[92:93], s[16:17], v[200:201] op_sel_hi:[1,1,0]
	v_pk_fma_f32 v[94:95], v[94:95], s[16:17], v[200:201] op_sel_hi:[1,1,0]
	v_pk_fma_f32 v[96:97], v[96:97], s[16:17], v[200:201] op_sel_hi:[1,1,0]
	v_pk_fma_f32 v[98:99], v[98:99], s[16:17], v[200:201] op_sel_hi:[1,1,0]

.Lbm2_Ag2_skip:
	s_bfe_u32 s29, s48, 0x4000c
	s_cmp_eq_u32 s29, 0
	s_cbranch_scc1 .Lbm2_Ag3_skip
	s_waitcnt vmcnt(12)
	v_mfma_f32_16x16x32_fp8_fp8 v[84:87], v[2:3], v[186:187], 0
	v_mfma_f32_16x16x32_fp8_fp8 v[88:91], v[6:7], v[186:187], 0
	v_mfma_f32_16x16x32_fp8_fp8 v[92:95], v[12:13], v[186:187], 0
	v_mfma_f32_16x16x32_fp8_fp8 v[96:99], v[16:17], v[186:187], 0
	v_mfma_f32_16x16x32_fp8_fp8 v[84:87], v[4:5], v[188:189], v[84:87]
	v_mfma_f32_16x16x32_fp8_fp8 v[88:91], v[8:9], v[188:189], v[88:91]
	v_mfma_f32_16x16x32_fp8_fp8 v[92:95], v[14:15], v[188:189], v[92:95]
	v_mfma_f32_16x16x32_fp8_fp8 v[96:99], v[18:19], v[188:189], v[96:99]
	v_and_b32_e32 v199, s29, v244
	s_cmp_eq_u32 s14, 1
	v_cmp_ne_u32_e32 vcc, 0, v199
	s_cbranch_scc1 .Lbm2_Ag3_near
	v_add_f32_e32 v200, v81, v193
	v_cndmask_b32_e32 v200, v77, v200, vcc
	v_pk_fma_f32 v[84:85], v[84:85], s[16:17], v[200:201] op_sel_hi:[1,1,0]
	v_pk_fma_f32 v[86:87], v[86:87], s[16:17], v[200:201] op_sel_hi:[1,1,0]
	v_pk_fma_f32 v[88:89], v[88:89], s[16:17], v[200:201] op_sel_hi:[1,1,0]
	v_pk_fma_f32 v[90:91], v[90:91], s[16:17], v[200:201] op_sel_hi:[1,1,0]
	v_pk_fma_f32 v[92:93], v[92:93], s[16:17], v[200:201] op_sel_hi:[1,1,0]
	v_pk_fma_f32 v[94:95], v[94:95], s[16:17], v[200:201] op_sel_hi:[1,1,0]
	v_pk_fma_f32 v[96:97], v[96:97], s[16:17], v[200:201] op_sel_hi:[1,1,0]
	v_pk_fma_f32 v[98:99], v[98:99], s[16:17], v[200:201] op_sel_hi:[1,1,0]
	s_cmp_eq_u32 s35, 0
	s_cbranch_scc1 .Lbm2_Ag3_max
	v_exp_f32_e32 v84, v84
	v_exp_f32_e32 v85, v85
	v_exp_f32_e32 v86, v86
	v_exp_f32_e32 v87, v87
	v_exp_f32_e32 v88, v88
	v_exp_f32_e32 v89, v89
	v_exp_f32_e32 v90, v90
	v_exp_f32_e32 v91, v91
	v_exp_f32_e32 v92, v92
	v_exp_f32_e32 v93, v93
	v_exp_f32_e32 v94, v94
	v_exp_f32_e32 v95, v95
	v_exp_f32_e32 v96, v96
	v_exp_f32_e32 v97, v97
	v_exp_f32_e32 v98, v98
	v_exp_f32_e32 v99, v99
	v_pk_add_f32 v[248:249], v[84:85], v[86:87]
	v_pk_add_f32 v[248:249], v[248:249], v[88:89]
	v_pk_add_f32 v[248:249], v[248:249], v[90:91]
	v_pk_add_f32 v[248:249], v[248:249], v[92:93]
	v_pk_add_f32 v[248:249], v[248:249], v[94:95]
	v_pk_add_f32 v[248:249], v[248:249], v[96:97]
	v_pk_add_f32 v[248:249], v[248:249], v[98:99]
	v_add_f32_e32 v248, v248, v249
	v_cmp_lt_f32_e32 vcc, 0x43800000, v248
	s_cbranch_vccnz .Lbm2_Ag3_redo
	v_cvt_pk_fp8_f32 v84, v84, v85
	v_cvt_pk_fp8_f32 v85, v88, v89
	v_cvt_pk_fp8_f32 v84, v86, v87 op_sel:[0,0,1]
	v_cvt_pk_fp8_f32 v85, v90, v91 op_sel:[0,0,1]
	v_cvt_pk_fp8_f32 v86, v92, v93
	v_cvt_pk_fp8_f32 v87, v96, v97
	v_cvt_pk_fp8_f32 v86, v94, v95 op_sel:[0,0,1]
	v_cvt_pk_fp8_f32 v87, v98, v99 op_sel:[0,0,1]
	v_add_f32_e32 v197, v197, v248
	s_waitcnt vmcnt(8)
	s_nop 1
	v_mfma_f32_16x16x32_fp8_fp8 v[148:151], v[36:37], v[84:85], v[148:151]
	v_mfma_f32_16x16x32_fp8_fp8 v[152:155], v[38:39], v[84:85], v[152:155]
	v_mfma_f32_16x16x32_fp8_fp8 v[156:159], v[40:41], v[84:85], v[156:159]
	v_mfma_f32_16x16x32_fp8_fp8 v[160:163], v[42:43], v[84:85], v[160:163]
	v_mfma_f32_16x16x32_fp8_fp8 v[148:151], v[44:45], v[86:87], v[148:151]
	v_mfma_f32_16x16x32_fp8_fp8 v[152:155], v[46:47], v[86:87], v[152:155]
	v_mfma_f32_16x16x32_fp8_fp8 v[156:159], v[48:49], v[86:87], v[156:159]
	v_mfma_f32_16x16x32_fp8_fp8 v[160:163], v[50:51], v[86:87], v[160:163]
	s_branch .Lbm2_Ag3_skip
.Lbm2_Ag3_redo:
	v_mfma_f32_16x16x32_fp8_fp8 v[84:87], v[2:3], v[186:187], 0
	v_mfma_f32_16x16x32_fp8_fp8 v[88:91], v[6:7], v[186:187], 0
	v_mfma_f32_16x16x32_fp8_fp8 v[92:95], v[12:13], v[186:187], 0
	v_mfma_f32_16x16x32_fp8_fp8 v[96:99], v[16:17], v[186:187], 0
	v_mfma_f32_16x16x32_fp8_fp8 v[84:87], v[4:5], v[188:189], v[84:87]
	v_mfma_f32_16x16x32_fp8_fp8 v[88:91], v[8:9], v[188:189], v[88:91]
	v_mfma_f32_16x16x32_fp8_fp8 v[92:95], v[14:15], v[188:189], v[92:95]
	v_mfma_f32_16x16x32_fp8_fp8 v[96:99], v[18:19], v[188:189], v[96:99]
	s_nop 7
	v_pk_fma_f32 v[84:85], v[84:85], s[16:17], v[200:201] op_sel_hi:[1,1,0]
	v_pk_fma_f32 v[86:87], v[86:87], s[16:17], v[200:201] op_sel_hi:[1,1,0]
	v_pk_fma_f32 v[88:89], v[88:89], s[16:17], v[200:201] op_sel_hi:[1,1,0]
	v_pk_fma_f32 v[90:91], v[90:91], s[16:17], v[200:201] op_sel_hi:[1,1,0]
	v_pk_fma_f32 v[92:93], v[92:93], s[16:17], v[200:201] op_sel_hi:[1,1,0]
	v_pk_fma_f32 v[94:95], v[94:95], s[16:17], v[200:201] op_sel_hi:[1,1,0]
	v_pk_fma_f32 v[96:97], v[96:97], s[16:17], v[200:201] op_sel_hi:[1,1,0]
	v_pk_fma_f32 v[98:99], v[98:99], s[16:17], v[200:201] op_sel_hi:[1,1,0]

.Lbm2_blkB:
	s_lshl_b32 s12, s15, 12
	s_add_u32 s30, s46, s12
	s_addc_u32 s31, s47, 0
	global_load_dwordx4 v[2:5], v79, s[30:31]
	global_load_dwordx4 v[6:9], v79, s[30:31] offset:1024
	global_load_dwordx4 v[12:15], v79, s[30:31] offset:2048
	global_load_dwordx4 v[16:19], v79, s[30:31] offset:3072
	s_lshl_b32 s12, s15, 12
	s_add_u32 s30, s62, s12
	s_addc_u32 s31, s63, 0
	global_load_dwordx4 v[36:39], v79, s[30:31]
	global_load_dwordx4 v[40:43], v79, s[30:31] offset:1024
	global_load_dwordx4 v[44:47], v79, s[30:31] offset:2048
	global_load_dwordx4 v[48:51], v79, s[30:31] offset:3072
	s_add_i32 s14, s35, 2
	s_add_i32 s13, s25, -1
	s_min_i32 s14, s14, s13
	s_lshl_b32 s13, s14, 2
	s_add_i32 s13, s13, s96
	v_mov_b32_e32 v76, s13
	ds_read_b32 v76, v76 offset:16384
	s_cmp_ge_i32 s54, s21
	s_cselect_b32 s14, 1, 0
	s_bfe_u32 s29, s48, 0x40000
	s_cmp_eq_u32 s29, 0
	s_cbranch_scc1 .Lbm2_Bg0_skip
	s_waitcnt vmcnt(12)
	v_mfma_f32_16x16x32_fp8_fp8 v[84:87], v[20:21], v[164:165], 0
	v_mfma_f32_16x16x32_fp8_fp8 v[88:91], v[24:25], v[164:165], 0
	v_mfma_f32_16x16x32_fp8_fp8 v[92:95], v[28:29], v[164:165], 0
	v_mfma_f32_16x16x32_fp8_fp8 v[96:99], v[32:33], v[164:165], 0
	v_mfma_f32_16x16x32_fp8_fp8 v[84:87], v[22:23], v[166:167], v[84:87]
	v_mfma_f32_16x16x32_fp8_fp8 v[88:91], v[26:27], v[166:167], v[88:91]
	v_mfma_f32_16x16x32_fp8_fp8 v[92:95], v[30:31], v[166:167], v[92:95]
	v_mfma_f32_16x16x32_fp8_fp8 v[96:99], v[34:35], v[166:167], v[96:99]
	v_and_b32_e32 v199, s29, v244
	s_cmp_eq_u32 s14, 1
	v_cmp_ne_u32_e32 vcc, 0, v199
	s_cbranch_scc1 .Lbm2_Bg0_near
	v_add_f32_e32 v200, v81, v190
	v_cndmask_b32_e32 v200, v77, v200, vcc
	v_pk_fma_f32 v[84:85], v[84:85], s[16:17], v[200:201] op_sel_hi:[1,1,0]
	v_pk_fma_f32 v[86:87], v[86:87], s[16:17], v[200:201] op_sel_hi:[1,1,0]
	v_pk_fma_f32 v[88:89], v[88:89], s[16:17], v[200:201] op_sel_hi:[1,1,0]
	v_pk_fma_f32 v[90:91], v[90:91], s[16:17], v[200:201] op_sel_hi:[1,1,0]
	v_pk_fma_f32 v[92:93], v[92:93], s[16:17], v[200:201] op_sel_hi:[1,1,0]
	v_pk_fma_f32 v[94:95], v[94:95], s[16:17], v[200:201] op_sel_hi:[1,1,0]
	v_pk_fma_f32 v[96:97], v[96:97], s[16:17], v[200:201] op_sel_hi:[1,1,0]
	v_pk_fma_f32 v[98:99], v[98:99], s[16:17], v[200:201] op_sel_hi:[1,1,0]
	s_cmp_eq_u32 s35, 0
	s_cbranch_scc1 .Lbm2_Bg0_max
	v_exp_f32_e32 v84, v84
	v_exp_f32_e32 v85, v85
	v_exp_f32_e32 v86, v86
	v_exp_f32_e32 v87, v87
	v_exp_f32_e32 v88, v88
	v_exp_f32_e32 v89, v89
	v_exp_f32_e32 v90, v90
	v_exp_f32_e32 v91, v91
	v_exp_f32_e32 v92, v92
	v_exp_f32_e32 v93, v93
	v_exp_f32_e32 v94, v94
	v_exp_f32_e32 v95, v95
	v_exp_f32_e32 v96, v96
	v_exp_f32_e32 v97, v97
	v_exp_f32_e32 v98, v98
	v_exp_f32_e32 v99, v99
	v_pk_add_f32 v[248:249], v[84:85], v[86:87]
	v_pk_add_f32 v[248:249], v[248:249], v[88:89]
	v_pk_add_f32 v[248:249], v[248:249], v[90:91]
	v_pk_add_f32 v[248:249], v[248:249], v[92:93]
	v_pk_add_f32 v[248:249], v[248:249], v[94:95]
	v_pk_add_f32 v[248:249], v[248:249], v[96:97]
	v_pk_add_f32 v[248:249], v[248:249], v[98:99]
	v_add_f32_e32 v248, v248, v249
	v_cmp_lt_f32_e32 vcc, 0x43800000, v248
	s_cbranch_vccnz .Lbm2_Bg0_redo
	v_cvt_pk_fp8_f32 v84, v84, v85
	v_cvt_pk_fp8_f32 v85, v88, v89
	v_cvt_pk_fp8_f32 v84, v86, v87 op_sel:[0,0,1]
	v_cvt_pk_fp8_f32 v85, v90, v91 op_sel:[0,0,1]
	v_cvt_pk_fp8_f32 v86, v92, v93
	v_cvt_pk_fp8_f32 v87, v96, v97
	v_cvt_pk_fp8_f32 v86, v94, v95 op_sel:[0,0,1]
	v_cvt_pk_fp8_f32 v87, v98, v99 op_sel:[0,0,1]
	v_add_f32_e32 v194, v194, v248
	s_waitcnt vmcnt(8)
	s_nop 1
	v_mfma_f32_16x16x32_fp8_fp8 v[100:103], v[52:53], v[84:85], v[100:103]
	v_mfma_f32_16x16x32_fp8_fp8 v[104:107], v[54:55], v[84:85], v[104:107]
	v_mfma_f32_16x16x32_fp8_fp8 v[108:111], v[56:57], v[84:85], v[108:111]
	v_mfma_f32_16x16x32_fp8_fp8 v[112:115], v[58:59], v[84:85], v[112:115]
	v_mfma_f32_16x16x32_fp8_fp8 v[100:103], v[60:61], v[86:87], v[100:103]
	v_mfma_f32_16x16x32_fp8_fp8 v[104:107], v[62:63], v[86:87], v[104:107]
	v_mfma_f32_16x16x32_fp8_fp8 v[108:111], v[64:65], v[86:87], v[108:111]
	v_mfma_f32_16x16x32_fp8_fp8 v[112:115], v[66:67], v[86:87], v[112:115]
	s_branch .Lbm2_Bg0_skip
.Lbm2_Bg0_redo:
	v_mfma_f32_16x16x32_fp8_fp8 v[84:87], v[20:21], v[164:165], 0
	v_mfma_f32_16x16x32_fp8_fp8 v[88:91], v[24:25], v[164:165], 0
	v_mfma_f32_16x16x32_fp8_fp8 v[92:95], v[28:29], v[164:165], 0
	v_mfma_f32_16x16x32_fp8_fp8 v[96:99], v[32:33], v[164:165], 0
	v_mfma_f32_16x16x32_fp8_fp8 v[84:87], v[22:23], v[166:167], v[84:87]
	v_mfma_f32_16x16x32_fp8_fp8 v[88:91], v[26:27], v[166:167], v[88:91]
	v_mfma_f32_16x16x32_fp8_fp8 v[92:95], v[30:31], v[166:167], v[92:95]
	v_mfma_f32_16x16x32_fp8_fp8 v[96:99], v[34:35], v[166:167], v[96:99]
	s_nop 7
	v_pk_fma_f32 v[84:85], v[84:85], s[16:17], v[200:201] op_sel_hi:[1,1,0]
	v_pk_fma_f32 v[86:87], v[86:87], s[16:17], v[200:201] op_sel_hi:[1,1,0]
	v_pk_fma_f32 v[88:89], v[88:89], s[16:17], v[200:201] op_sel_hi:[1,1,0]
	v_pk_fma_f32 v[90:91], v[90:91], s[16:17], v[200:201] op_sel_hi:[1,1,0]
	v_pk_fma_f32 v[92:93], v[92:93], s[16:17], v[200:201] op_sel_hi:[1,1,0]
	v_pk_fma_f32 v[94:95], v[94:95], s[16:17], v[200:201] op_sel_hi:[1,1,0]
	v_pk_fma_f32 v[96:97], v[96:97], s[16:17], v[200:201] op_sel_hi:[1,1,0]
	v_pk_fma_f32 v[98:99], v[98:99], s[16:17], v[200:201] op_sel_hi:[1,1,0]

.Lbm2_Bg0_skip:
	s_bfe_u32 s29, s48, 0x40004
	s_cmp_eq_u32 s29, 0
	s_cbranch_scc1 .Lbm2_Bg1_skip
	s_waitcnt vmcnt(12)
	v_mfma_f32_16x16x32_fp8_fp8 v[84:87], v[20:21], v[168:169], 0
	v_mfma_f32_16x16x32_fp8_fp8 v[88:91], v[24:25], v[168:169], 0
	v_mfma_f32_16x16x32_fp8_fp8 v[92:95], v[28:29], v[168:169], 0
	v_mfma_f32_16x16x32_fp8_fp8 v[96:99], v[32:33], v[168:169], 0
	v_mfma_f32_16x16x32_fp8_fp8 v[84:87], v[22:23], v[170:171], v[84:87]
	v_mfma_f32_16x16x32_fp8_fp8 v[88:91], v[26:27], v[170:171], v[88:91]
	v_mfma_f32_16x16x32_fp8_fp8 v[92:95], v[30:31], v[170:171], v[92:95]
	v_mfma_f32_16x16x32_fp8_fp8 v[96:99], v[34:35], v[170:171], v[96:99]
	v_and_b32_e32 v199, s29, v244
	s_cmp_eq_u32 s14, 1
	v_cmp_ne_u32_e32 vcc, 0, v199
	s_cbranch_scc1 .Lbm2_Bg1_near
	v_add_f32_e32 v200, v81, v191
	v_cndmask_b32_e32 v200, v77, v200, vcc
	v_pk_fma_f32 v[84:85], v[84:85], s[16:17], v[200:201] op_sel_hi:[1,1,0]
	v_pk_fma_f32 v[86:87], v[86:87], s[16:17], v[200:201] op_sel_hi:[1,1,0]
	v_pk_fma_f32 v[88:89], v[88:89], s[16:17], v[200:201] op_sel_hi:[1,1,0]
	v_pk_fma_f32 v[90:91], v[90:91], s[16:17], v[200:201] op_sel_hi:[1,1,0]
	v_pk_fma_f32 v[92:93], v[92:93], s[16:17], v[200:201] op_sel_hi:[1,1,0]
	v_pk_fma_f32 v[94:95], v[94:95], s[16:17], v[200:201] op_sel_hi:[1,1,0]
	v_pk_fma_f32 v[96:97], v[96:97], s[16:17], v[200:201] op_sel_hi:[1,1,0]
	v_pk_fma_f32 v[98:99], v[98:99], s[16:17], v[200:201] op_sel_hi:[1,1,0]
	s_cmp_eq_u32 s35, 0
	s_cbranch_scc1 .Lbm2_Bg1_max
	v_exp_f32_e32 v84, v84
	v_exp_f32_e32 v85, v85
	v_exp_f32_e32 v86, v86
	v_exp_f32_e32 v87, v87
	v_exp_f32_e32 v88, v88
	v_exp_f32_e32 v89, v89
	v_exp_f32_e32 v90, v90
	v_exp_f32_e32 v91, v91
	v_exp_f32_e32 v92, v92
	v_exp_f32_e32 v93, v93
	v_exp_f32_e32 v94, v94
	v_exp_f32_e32 v95, v95
	v_exp_f32_e32 v96, v96
	v_exp_f32_e32 v97, v97
	v_exp_f32_e32 v98, v98
	v_exp_f32_e32 v99, v99
	v_pk_add_f32 v[248:249], v[84:85], v[86:87]
	v_pk_add_f32 v[248:249], v[248:249], v[88:89]
	v_pk_add_f32 v[248:249], v[248:249], v[90:91]
	v_pk_add_f32 v[248:249], v[248:249], v[92:93]
	v_pk_add_f32 v[248:249], v[248:249], v[94:95]
	v_pk_add_f32 v[248:249], v[248:249], v[96:97]
	v_pk_add_f32 v[248:249], v[248:249], v[98:99]
	v_add_f32_e32 v248, v248, v249
	v_cmp_lt_f32_e32 vcc, 0x43800000, v248
	s_cbranch_vccnz .Lbm2_Bg1_redo
	v_cvt_pk_fp8_f32 v84, v84, v85
	v_cvt_pk_fp8_f32 v85, v88, v89
	v_cvt_pk_fp8_f32 v84, v86, v87 op_sel:[0,0,1]
	v_cvt_pk_fp8_f32 v85, v90, v91 op_sel:[0,0,1]
	v_cvt_pk_fp8_f32 v86, v92, v93
	v_cvt_pk_fp8_f32 v87, v96, v97
	v_cvt_pk_fp8_f32 v86, v94, v95 op_sel:[0,0,1]
	v_cvt_pk_fp8_f32 v87, v98, v99 op_sel:[0,0,1]
	v_add_f32_e32 v195, v195, v248
	s_waitcnt vmcnt(8)
	s_nop 1
	v_mfma_f32_16x16x32_fp8_fp8 v[116:119], v[52:53], v[84:85], v[116:119]
	v_mfma_f32_16x16x32_fp8_fp8 v[120:123], v[54:55], v[84:85], v[120:123]
	v_mfma_f32_16x16x32_fp8_fp8 v[124:127], v[56:57], v[84:85], v[124:127]
	v_mfma_f32_16x16x32_fp8_fp8 v[128:131], v[58:59], v[84:85], v[128:131]
	v_mfma_f32_16x16x32_fp8_fp8 v[116:119], v[60:61], v[86:87], v[116:119]
	v_mfma_f32_16x16x32_fp8_fp8 v[120:123], v[62:63], v[86:87], v[120:123]
	v_mfma_f32_16x16x32_fp8_fp8 v[124:127], v[64:65], v[86:87], v[124:127]
	v_mfma_f32_16x16x32_fp8_fp8 v[128:131], v[66:67], v[86:87], v[128:131]
	s_branch .Lbm2_Bg1_skip
.Lbm2_Bg1_redo:
	v_mfma_f32_16x16x32_fp8_fp8 v[84:87], v[20:21], v[168:169], 0
	v_mfma_f32_16x16x32_fp8_fp8 v[88:91], v[24:25], v[168:169], 0
	v_mfma_f32_16x16x32_fp8_fp8 v[92:95], v[28:29], v[168:169], 0
	v_mfma_f32_16x16x32_fp8_fp8 v[96:99], v[32:33], v[168:169], 0
	v_mfma_f32_16x16x32_fp8_fp8 v[84:87], v[22:23], v[170:171], v[84:87]
	v_mfma_f32_16x16x32_fp8_fp8 v[88:91], v[26:27], v[170:171], v[88:91]
	v_mfma_f32_16x16x32_fp8_fp8 v[92:95], v[30:31], v[170:171], v[92:95]
	v_mfma_f32_16x16x32_fp8_fp8 v[96:99], v[34:35], v[170:171], v[96:99]
	s_nop 7
	v_pk_fma_f32 v[84:85], v[84:85], s[16:17], v[200:201] op_sel_hi:[1,1,0]
	v_pk_fma_f32 v[86:87], v[86:87], s[16:17], v[200:201] op_sel_hi:[1,1,0]
	v_pk_fma_f32 v[88:89], v[88:89], s[16:17], v[200:201] op_sel_hi:[1,1,0]
	v_pk_fma_f32 v[90:91], v[90:91], s[16:17], v[200:201] op_sel_hi:[1,1,0]
	v_pk_fma_f32 v[92:93], v[92:93], s[16:17], v[200:201] op_sel_hi:[1,1,0]
	v_pk_fma_f32 v[94:95], v[94:95], s[16:17], v[200:201] op_sel_hi:[1,1,0]
	v_pk_fma_f32 v[96:97], v[96:97], s[16:17], v[200:201] op_sel_hi:[1,1,0]
	v_pk_fma_f32 v[98:99], v[98:99], s[16:17], v[200:201] op_sel_hi:[1,1,0]

.Lbm2_Bg1_skip:
	s_bfe_u32 s29, s48, 0x40008
	s_cmp_eq_u32 s29, 0
	s_cbranch_scc1 .Lbm2_Bg2_skip
	s_waitcnt vmcnt(12)
	v_mfma_f32_16x16x32_fp8_fp8 v[84:87], v[20:21], v[182:183], 0
	v_mfma_f32_16x16x32_fp8_fp8 v[88:91], v[24:25], v[182:183], 0
	v_mfma_f32_16x16x32_fp8_fp8 v[92:95], v[28:29], v[182:183], 0
	v_mfma_f32_16x16x32_fp8_fp8 v[96:99], v[32:33], v[182:183], 0
	v_mfma_f32_16x16x32_fp8_fp8 v[84:87], v[22:23], v[184:185], v[84:87]
	v_mfma_f32_16x16x32_fp8_fp8 v[88:91], v[26:27], v[184:185], v[88:91]
	v_mfma_f32_16x16x32_fp8_fp8 v[92:95], v[30:31], v[184:185], v[92:95]
	v_mfma_f32_16x16x32_fp8_fp8 v[96:99], v[34:35], v[184:185], v[96:99]
	v_and_b32_e32 v199, s29, v244
	s_cmp_eq_u32 s14, 1
	v_cmp_ne_u32_e32 vcc, 0, v199
	s_cbranch_scc1 .Lbm2_Bg2_near
	v_add_f32_e32 v200, v81, v192
	v_cndmask_b32_e32 v200, v77, v200, vcc
	v_pk_fma_f32 v[84:85], v[84:85], s[16:17], v[200:201] op_sel_hi:[1,1,0]
	v_pk_fma_f32 v[86:87], v[86:87], s[16:17], v[200:201] op_sel_hi:[1,1,0]
	v_pk_fma_f32 v[88:89], v[88:89], s[16:17], v[200:201] op_sel_hi:[1,1,0]
	v_pk_fma_f32 v[90:91], v[90:91], s[16:17], v[200:201] op_sel_hi:[1,1,0]
	v_pk_fma_f32 v[92:93], v[92:93], s[16:17], v[200:201] op_sel_hi:[1,1,0]
	v_pk_fma_f32 v[94:95], v[94:95], s[16:17], v[200:201] op_sel_hi:[1,1,0]
	v_pk_fma_f32 v[96:97], v[96:97], s[16:17], v[200:201] op_sel_hi:[1,1,0]
	v_pk_fma_f32 v[98:99], v[98:99], s[16:17], v[200:201] op_sel_hi:[1,1,0]
	s_cmp_eq_u32 s35, 0
	s_cbranch_scc1 .Lbm2_Bg2_max
	v_exp_f32_e32 v84, v84
	v_exp_f32_e32 v85, v85
	v_exp_f32_e32 v86, v86
	v_exp_f32_e32 v87, v87
	v_exp_f32_e32 v88, v88
	v_exp_f32_e32 v89, v89
	v_exp_f32_e32 v90, v90
	v_exp_f32_e32 v91, v91
	v_exp_f32_e32 v92, v92
	v_exp_f32_e32 v93, v93
	v_exp_f32_e32 v94, v94
	v_exp_f32_e32 v95, v95
	v_exp_f32_e32 v96, v96
	v_exp_f32_e32 v97, v97
	v_exp_f32_e32 v98, v98
	v_exp_f32_e32 v99, v99
	v_pk_add_f32 v[248:249], v[84:85], v[86:87]
	v_pk_add_f32 v[248:249], v[248:249], v[88:89]
	v_pk_add_f32 v[248:249], v[248:249], v[90:91]
	v_pk_add_f32 v[248:249], v[248:249], v[92:93]
	v_pk_add_f32 v[248:249], v[248:249], v[94:95]
	v_pk_add_f32 v[248:249], v[248:249], v[96:97]
	v_pk_add_f32 v[248:249], v[248:249], v[98:99]
	v_add_f32_e32 v248, v248, v249
	v_cmp_lt_f32_e32 vcc, 0x43800000, v248
	s_cbranch_vccnz .Lbm2_Bg2_redo
	v_cvt_pk_fp8_f32 v84, v84, v85
	v_cvt_pk_fp8_f32 v85, v88, v89
	v_cvt_pk_fp8_f32 v84, v86, v87 op_sel:[0,0,1]
	v_cvt_pk_fp8_f32 v85, v90, v91 op_sel:[0,0,1]
	v_cvt_pk_fp8_f32 v86, v92, v93
	v_cvt_pk_fp8_f32 v87, v96, v97
	v_cvt_pk_fp8_f32 v86, v94, v95 op_sel:[0,0,1]
	v_cvt_pk_fp8_f32 v87, v98, v99 op_sel:[0,0,1]
	v_add_f32_e32 v196, v196, v248
	s_waitcnt vmcnt(8)
	s_nop 1
	v_mfma_f32_16x16x32_fp8_fp8 v[132:135], v[52:53], v[84:85], v[132:135]
	v_mfma_f32_16x16x32_fp8_fp8 v[136:139], v[54:55], v[84:85], v[136:139]
	v_mfma_f32_16x16x32_fp8_fp8 v[140:143], v[56:57], v[84:85], v[140:143]
	v_mfma_f32_16x16x32_fp8_fp8 v[144:147], v[58:59], v[84:85], v[144:147]
	v_mfma_f32_16x16x32_fp8_fp8 v[132:135], v[60:61], v[86:87], v[132:135]
	v_mfma_f32_16x16x32_fp8_fp8 v[136:139], v[62:63], v[86:87], v[136:139]
	v_mfma_f32_16x16x32_fp8_fp8 v[140:143], v[64:65], v[86:87], v[140:143]
	v_mfma_f32_16x16x32_fp8_fp8 v[144:147], v[66:67], v[86:87], v[144:147]
	s_branch .Lbm2_Bg2_skip
.Lbm2_Bg2_redo:
	v_mfma_f32_16x16x32_fp8_fp8 v[84:87], v[20:21], v[182:183], 0
	v_mfma_f32_16x16x32_fp8_fp8 v[88:91], v[24:25], v[182:183], 0
	v_mfma_f32_16x16x32_fp8_fp8 v[92:95], v[28:29], v[182:183], 0
	v_mfma_f32_16x16x32_fp8_fp8 v[96:99], v[32:33], v[182:183], 0
	v_mfma_f32_16x16x32_fp8_fp8 v[84:87], v[22:23], v[184:185], v[84:87]
	v_mfma_f32_16x16x32_fp8_fp8 v[88:91], v[26:27], v[184:185], v[88:91]
	v_mfma_f32_16x16x32_fp8_fp8 v[92:95], v[30:31], v[184:185], v[92:95]
	v_mfma_f32_16x16x32_fp8_fp8 v[96:99], v[34:35], v[184:185], v[96:99]
	s_nop 7
	v_pk_fma_f32 v[84:85], v[84:85], s[16:17], v[200:201] op_sel_hi:[1,1,0]
	v_pk_fma_f32 v[86:87], v[86:87], s[16:17], v[200:201] op_sel_hi:[1,1,0]
	v_pk_fma_f32 v[88:89], v[88:89], s[16:17], v[200:201] op_sel_hi:[1,1,0]
	v_pk_fma_f32 v[90:91], v[90:91], s[16:17], v[200:201] op_sel_hi:[1,1,0]
	v_pk_fma_f32 v[92:93], v[92:93], s[16:17], v[200:201] op_sel_hi:[1,1,0]
	v_pk_fma_f32 v[94:95], v[94:95], s[16:17], v[200:201] op_sel_hi:[1,1,0]
	v_pk_fma_f32 v[96:97], v[96:97], s[16:17], v[200:201] op_sel_hi:[1,1,0]
	v_pk_fma_f32 v[98:99], v[98:99], s[16:17], v[200:201] op_sel_hi:[1,1,0]

.Lbm2_Bg2_skip:
	s_bfe_u32 s29, s48, 0x4000c
	s_cmp_eq_u32 s29, 0
	s_cbranch_scc1 .Lbm2_Bg3_skip
	s_waitcnt vmcnt(12)
	v_mfma_f32_16x16x32_fp8_fp8 v[84:87], v[20:21], v[186:187], 0
	v_mfma_f32_16x16x32_fp8_fp8 v[88:91], v[24:25], v[186:187], 0
	v_mfma_f32_16x16x32_fp8_fp8 v[92:95], v[28:29], v[186:187], 0
	v_mfma_f32_16x16x32_fp8_fp8 v[96:99], v[32:33], v[186:187], 0
	v_mfma_f32_16x16x32_fp8_fp8 v[84:87], v[22:23], v[188:189], v[84:87]
	v_mfma_f32_16x16x32_fp8_fp8 v[88:91], v[26:27], v[188:189], v[88:91]
	v_mfma_f32_16x16x32_fp8_fp8 v[92:95], v[30:31], v[188:189], v[92:95]
	v_mfma_f32_16x16x32_fp8_fp8 v[96:99], v[34:35], v[188:189], v[96:99]
	v_and_b32_e32 v199, s29, v244
	s_cmp_eq_u32 s14, 1
	v_cmp_ne_u32_e32 vcc, 0, v199
	s_cbranch_scc1 .Lbm2_Bg3_near
	v_add_f32_e32 v200, v81, v193
	v_cndmask_b32_e32 v200, v77, v200, vcc
	v_pk_fma_f32 v[84:85], v[84:85], s[16:17], v[200:201] op_sel_hi:[1,1,0]
	v_pk_fma_f32 v[86:87], v[86:87], s[16:17], v[200:201] op_sel_hi:[1,1,0]
	v_pk_fma_f32 v[88:89], v[88:89], s[16:17], v[200:201] op_sel_hi:[1,1,0]
	v_pk_fma_f32 v[90:91], v[90:91], s[16:17], v[200:201] op_sel_hi:[1,1,0]
	v_pk_fma_f32 v[92:93], v[92:93], s[16:17], v[200:201] op_sel_hi:[1,1,0]
	v_pk_fma_f32 v[94:95], v[94:95], s[16:17], v[200:201] op_sel_hi:[1,1,0]
	v_pk_fma_f32 v[96:97], v[96:97], s[16:17], v[200:201] op_sel_hi:[1,1,0]
	v_pk_fma_f32 v[98:99], v[98:99], s[16:17], v[200:201] op_sel_hi:[1,1,0]
	s_cmp_eq_u32 s35, 0
	s_cbranch_scc1 .Lbm2_Bg3_max
	v_exp_f32_e32 v84, v84
	v_exp_f32_e32 v85, v85
	v_exp_f32_e32 v86, v86
	v_exp_f32_e32 v87, v87
	v_exp_f32_e32 v88, v88
	v_exp_f32_e32 v89, v89
	v_exp_f32_e32 v90, v90
	v_exp_f32_e32 v91, v91
	v_exp_f32_e32 v92, v92
	v_exp_f32_e32 v93, v93
	v_exp_f32_e32 v94, v94
	v_exp_f32_e32 v95, v95
	v_exp_f32_e32 v96, v96
	v_exp_f32_e32 v97, v97
	v_exp_f32_e32 v98, v98
	v_exp_f32_e32 v99, v99
	v_pk_add_f32 v[248:249], v[84:85], v[86:87]
	v_pk_add_f32 v[248:249], v[248:249], v[88:89]
	v_pk_add_f32 v[248:249], v[248:249], v[90:91]
	v_pk_add_f32 v[248:249], v[248:249], v[92:93]
	v_pk_add_f32 v[248:249], v[248:249], v[94:95]
	v_pk_add_f32 v[248:249], v[248:249], v[96:97]
	v_pk_add_f32 v[248:249], v[248:249], v[98:99]
	v_add_f32_e32 v248, v248, v249
	v_cmp_lt_f32_e32 vcc, 0x43800000, v248
	s_cbranch_vccnz .Lbm2_Bg3_redo
	v_cvt_pk_fp8_f32 v84, v84, v85
	v_cvt_pk_fp8_f32 v85, v88, v89
	v_cvt_pk_fp8_f32 v84, v86, v87 op_sel:[0,0,1]
	v_cvt_pk_fp8_f32 v85, v90, v91 op_sel:[0,0,1]
	v_cvt_pk_fp8_f32 v86, v92, v93
	v_cvt_pk_fp8_f32 v87, v96, v97
	v_cvt_pk_fp8_f32 v86, v94, v95 op_sel:[0,0,1]
	v_cvt_pk_fp8_f32 v87, v98, v99 op_sel:[0,0,1]
	v_add_f32_e32 v197, v197, v248
	s_waitcnt vmcnt(8)
	s_nop 1
	v_mfma_f32_16x16x32_fp8_fp8 v[148:151], v[52:53], v[84:85], v[148:151]
	v_mfma_f32_16x16x32_fp8_fp8 v[152:155], v[54:55], v[84:85], v[152:155]
	v_mfma_f32_16x16x32_fp8_fp8 v[156:159], v[56:57], v[84:85], v[156:159]
	v_mfma_f32_16x16x32_fp8_fp8 v[160:163], v[58:59], v[84:85], v[160:163]
	v_mfma_f32_16x16x32_fp8_fp8 v[148:151], v[60:61], v[86:87], v[148:151]
	v_mfma_f32_16x16x32_fp8_fp8 v[152:155], v[62:63], v[86:87], v[152:155]
	v_mfma_f32_16x16x32_fp8_fp8 v[156:159], v[64:65], v[86:87], v[156:159]
	v_mfma_f32_16x16x32_fp8_fp8 v[160:163], v[66:67], v[86:87], v[160:163]
	s_branch .Lbm2_Bg3_skip
.Lbm2_Bg3_redo:
	v_mfma_f32_16x16x32_fp8_fp8 v[84:87], v[20:21], v[186:187], 0
	v_mfma_f32_16x16x32_fp8_fp8 v[88:91], v[24:25], v[186:187], 0
	v_mfma_f32_16x16x32_fp8_fp8 v[92:95], v[28:29], v[186:187], 0
	v_mfma_f32_16x16x32_fp8_fp8 v[96:99], v[32:33], v[186:187], 0
	v_mfma_f32_16x16x32_fp8_fp8 v[84:87], v[22:23], v[188:189], v[84:87]
	v_mfma_f32_16x16x32_fp8_fp8 v[88:91], v[26:27], v[188:189], v[88:91]
	v_mfma_f32_16x16x32_fp8_fp8 v[92:95], v[30:31], v[188:189], v[92:95]
	v_mfma_f32_16x16x32_fp8_fp8 v[96:99], v[34:35], v[188:189], v[96:99]
	s_nop 7
	v_pk_fma_f32 v[84:85], v[84:85], s[16:17], v[200:201] op_sel_hi:[1,1,0]
	v_pk_fma_f32 v[86:87], v[86:87], s[16:17], v[200:201] op_sel_hi:[1,1,0]
	v_pk_fma_f32 v[88:89], v[88:89], s[16:17], v[200:201] op_sel_hi:[1,1,0]
	v_pk_fma_f32 v[90:91], v[90:91], s[16:17], v[200:201] op_sel_hi:[1,1,0]
	v_pk_fma_f32 v[92:93], v[92:93], s[16:17], v[200:201] op_sel_hi:[1,1,0]
	v_pk_fma_f32 v[94:95], v[94:95], s[16:17], v[200:201] op_sel_hi:[1,1,0]
	v_pk_fma_f32 v[96:97], v[96:97], s[16:17], v[200:201] op_sel_hi:[1,1,0]
	v_pk_fma_f32 v[98:99], v[98:99], s[16:17], v[200:201] op_sel_hi:[1,1,0]

.Lbm3_nostag:
.Lbm3_blkA:
	s_lshl_b32 s29, s27, 12
	s_add_u32 s30, s40, s29
	s_addc_u32 s31, s41, 0
	global_load_dwordx4 v[20:23], v79, s[30:31]
	global_load_dwordx4 v[24:27], v79, s[30:31] offset:1024
	global_load_dwordx4 v[28:31], v79, s[30:31] offset:2048
	global_load_dwordx4 v[32:35], v79, s[30:31] offset:3072
	s_lshl_b32 s29, s27, 12
	s_add_u32 s30, s62, s29
	s_addc_u32 s31, s63, 0
	global_load_dwordx4 v[52:55], v79, s[30:31]
	global_load_dwordx4 v[56:59], v79, s[30:31] offset:1024
	global_load_dwordx4 v[60:63], v79, s[30:31] offset:2048
	global_load_dwordx4 v[64:67], v79, s[30:31] offset:3072
	s_add_i32 s50, s35, 2
	s_add_i32 s9, s25, -1
	s_min_i32 s50, s50, s9
	s_lshl_b32 s9, s50, 2
	s_add_i32 s9, s9, s46
	v_mov_b32_e32 v76, s9
	ds_read_b32 v76, v76 offset:16384
	s_cmp_ge_i32 s38, s21
	s_cselect_b32 s50, 1, 0
	s_bfe_u32 s29, s48, 0x40000
	s_cmp_eq_u32 s29, 0
	s_cbranch_scc1 .Lbm3_Ag0_skip
	s_waitcnt vmcnt(12)
	v_mfma_f32_16x16x32_fp8_fp8 v[84:87], v[2:3], v[164:165], 0
	v_mfma_f32_16x16x32_fp8_fp8 v[88:91], v[6:7], v[164:165], 0
	v_mfma_f32_16x16x32_fp8_fp8 v[92:95], v[12:13], v[164:165], 0
	v_mfma_f32_16x16x32_fp8_fp8 v[96:99], v[16:17], v[164:165], 0
	v_mfma_f32_16x16x32_fp8_fp8 v[84:87], v[4:5], v[166:167], v[84:87]
	v_mfma_f32_16x16x32_fp8_fp8 v[88:91], v[8:9], v[166:167], v[88:91]
	v_mfma_f32_16x16x32_fp8_fp8 v[92:95], v[14:15], v[166:167], v[92:95]
	v_mfma_f32_16x16x32_fp8_fp8 v[96:99], v[18:19], v[166:167], v[96:99]
	v_and_b32_e32 v199, s29, v244
	s_cmp_eq_u32 s50, 1
	v_cmp_ne_u32_e32 vcc, 0, v199
	s_cbranch_scc1 .Lbm3_Ag0_near
	v_add_f32_e32 v200, v81, v190
	v_cndmask_b32_e32 v200, v77, v200, vcc
	v_pk_fma_f32 v[84:85], v[84:85], s[10:11], v[200:201] op_sel_hi:[1,1,0]
	v_pk_fma_f32 v[86:87], v[86:87], s[10:11], v[200:201] op_sel_hi:[1,1,0]
	v_pk_fma_f32 v[88:89], v[88:89], s[10:11], v[200:201] op_sel_hi:[1,1,0]
	v_pk_fma_f32 v[90:91], v[90:91], s[10:11], v[200:201] op_sel_hi:[1,1,0]
	v_pk_fma_f32 v[92:93], v[92:93], s[10:11], v[200:201] op_sel_hi:[1,1,0]
	v_pk_fma_f32 v[94:95], v[94:95], s[10:11], v[200:201] op_sel_hi:[1,1,0]
	v_pk_fma_f32 v[96:97], v[96:97], s[10:11], v[200:201] op_sel_hi:[1,1,0]
	v_pk_fma_f32 v[98:99], v[98:99], s[10:11], v[200:201] op_sel_hi:[1,1,0]
	s_cmp_eq_u32 s35, 0
	s_cbranch_scc1 .Lbm3_Ag0_max
	v_exp_f32_e32 v84, v84
	v_exp_f32_e32 v85, v85
	v_exp_f32_e32 v86, v86
	v_exp_f32_e32 v87, v87
	v_exp_f32_e32 v88, v88
	v_exp_f32_e32 v89, v89
	v_exp_f32_e32 v90, v90
	v_exp_f32_e32 v91, v91
	v_exp_f32_e32 v92, v92
	v_exp_f32_e32 v93, v93
	v_exp_f32_e32 v94, v94
	v_exp_f32_e32 v95, v95
	v_exp_f32_e32 v96, v96
	v_exp_f32_e32 v97, v97
	v_exp_f32_e32 v98, v98
	v_exp_f32_e32 v99, v99
	v_pk_add_f32 v[248:249], v[84:85], v[86:87]
	v_pk_add_f32 v[248:249], v[248:249], v[88:89]
	v_pk_add_f32 v[248:249], v[248:249], v[90:91]
	v_pk_add_f32 v[248:249], v[248:249], v[92:93]
	v_pk_add_f32 v[248:249], v[248:249], v[94:95]
	v_pk_add_f32 v[248:249], v[248:249], v[96:97]
	v_pk_add_f32 v[248:249], v[248:249], v[98:99]
	v_add_f32_e32 v248, v248, v249
	v_cmp_lt_f32_e32 vcc, 0x43800000, v248
	s_cbranch_vccnz .Lbm3_Ag0_redo
	v_cvt_pk_fp8_f32 v84, v84, v85
	v_cvt_pk_fp8_f32 v85, v88, v89
	v_cvt_pk_fp8_f32 v84, v86, v87 op_sel:[0,0,1]
	v_cvt_pk_fp8_f32 v85, v90, v91 op_sel:[0,0,1]
	v_cvt_pk_fp8_f32 v86, v92, v93
	v_cvt_pk_fp8_f32 v87, v96, v97
	v_cvt_pk_fp8_f32 v86, v94, v95 op_sel:[0,0,1]
	v_cvt_pk_fp8_f32 v87, v98, v99 op_sel:[0,0,1]
	v_add_f32_e32 v194, v194, v248
	s_waitcnt vmcnt(8)
	s_nop 1
	v_mfma_f32_16x16x32_fp8_fp8 v[100:103], v[36:37], v[84:85], v[100:103]
	v_mfma_f32_16x16x32_fp8_fp8 v[104:107], v[38:39], v[84:85], v[104:107]
	v_mfma_f32_16x16x32_fp8_fp8 v[108:111], v[40:41], v[84:85], v[108:111]
	v_mfma_f32_16x16x32_fp8_fp8 v[112:115], v[42:43], v[84:85], v[112:115]
	v_mfma_f32_16x16x32_fp8_fp8 v[100:103], v[44:45], v[86:87], v[100:103]
	v_mfma_f32_16x16x32_fp8_fp8 v[104:107], v[46:47], v[86:87], v[104:107]
	v_mfma_f32_16x16x32_fp8_fp8 v[108:111], v[48:49], v[86:87], v[108:111]
	v_mfma_f32_16x16x32_fp8_fp8 v[112:115], v[50:51], v[86:87], v[112:115]
	s_branch .Lbm3_Ag0_skip
.Lbm3_Ag0_redo:
	v_mfma_f32_16x16x32_fp8_fp8 v[84:87], v[2:3], v[164:165], 0
	v_mfma_f32_16x16x32_fp8_fp8 v[88:91], v[6:7], v[164:165], 0
	v_mfma_f32_16x16x32_fp8_fp8 v[92:95], v[12:13], v[164:165], 0
	v_mfma_f32_16x16x32_fp8_fp8 v[96:99], v[16:17], v[164:165], 0
	v_mfma_f32_16x16x32_fp8_fp8 v[84:87], v[4:5], v[166:167], v[84:87]
	v_mfma_f32_16x16x32_fp8_fp8 v[88:91], v[8:9], v[166:167], v[88:91]
	v_mfma_f32_16x16x32_fp8_fp8 v[92:95], v[14:15], v[166:167], v[92:95]
	v_mfma_f32_16x16x32_fp8_fp8 v[96:99], v[18:19], v[166:167], v[96:99]
	s_nop 7
	v_pk_fma_f32 v[84:85], v[84:85], s[10:11], v[200:201] op_sel_hi:[1,1,0]
	v_pk_fma_f32 v[86:87], v[86:87], s[10:11], v[200:201] op_sel_hi:[1,1,0]
	v_pk_fma_f32 v[88:89], v[88:89], s[10:11], v[200:201] op_sel_hi:[1,1,0]
	v_pk_fma_f32 v[90:91], v[90:91], s[10:11], v[200:201] op_sel_hi:[1,1,0]
	v_pk_fma_f32 v[92:93], v[92:93], s[10:11], v[200:201] op_sel_hi:[1,1,0]
	v_pk_fma_f32 v[94:95], v[94:95], s[10:11], v[200:201] op_sel_hi:[1,1,0]
	v_pk_fma_f32 v[96:97], v[96:97], s[10:11], v[200:201] op_sel_hi:[1,1,0]
	v_pk_fma_f32 v[98:99], v[98:99], s[10:11], v[200:201] op_sel_hi:[1,1,0]

.Lbm3_Ag0_skip:
	s_bfe_u32 s29, s48, 0x40004
	s_cmp_eq_u32 s29, 0
	s_cbranch_scc1 .Lbm3_Ag1_skip
	s_waitcnt vmcnt(12)
	v_mfma_f32_16x16x32_fp8_fp8 v[84:87], v[2:3], v[168:169], 0
	v_mfma_f32_16x16x32_fp8_fp8 v[88:91], v[6:7], v[168:169], 0
	v_mfma_f32_16x16x32_fp8_fp8 v[92:95], v[12:13], v[168:169], 0
	v_mfma_f32_16x16x32_fp8_fp8 v[96:99], v[16:17], v[168:169], 0
	v_mfma_f32_16x16x32_fp8_fp8 v[84:87], v[4:5], v[170:171], v[84:87]
	v_mfma_f32_16x16x32_fp8_fp8 v[88:91], v[8:9], v[170:171], v[88:91]
	v_mfma_f32_16x16x32_fp8_fp8 v[92:95], v[14:15], v[170:171], v[92:95]
	v_mfma_f32_16x16x32_fp8_fp8 v[96:99], v[18:19], v[170:171], v[96:99]
	v_and_b32_e32 v199, s29, v244
	s_cmp_eq_u32 s50, 1
	v_cmp_ne_u32_e32 vcc, 0, v199
	s_cbranch_scc1 .Lbm3_Ag1_near
	v_add_f32_e32 v200, v81, v191
	v_cndmask_b32_e32 v200, v77, v200, vcc
	v_pk_fma_f32 v[84:85], v[84:85], s[10:11], v[200:201] op_sel_hi:[1,1,0]
	v_pk_fma_f32 v[86:87], v[86:87], s[10:11], v[200:201] op_sel_hi:[1,1,0]
	v_pk_fma_f32 v[88:89], v[88:89], s[10:11], v[200:201] op_sel_hi:[1,1,0]
	v_pk_fma_f32 v[90:91], v[90:91], s[10:11], v[200:201] op_sel_hi:[1,1,0]
	v_pk_fma_f32 v[92:93], v[92:93], s[10:11], v[200:201] op_sel_hi:[1,1,0]
	v_pk_fma_f32 v[94:95], v[94:95], s[10:11], v[200:201] op_sel_hi:[1,1,0]
	v_pk_fma_f32 v[96:97], v[96:97], s[10:11], v[200:201] op_sel_hi:[1,1,0]
	v_pk_fma_f32 v[98:99], v[98:99], s[10:11], v[200:201] op_sel_hi:[1,1,0]
	s_cmp_eq_u32 s35, 0
	s_cbranch_scc1 .Lbm3_Ag1_max
	v_exp_f32_e32 v84, v84
	v_exp_f32_e32 v85, v85
	v_exp_f32_e32 v86, v86
	v_exp_f32_e32 v87, v87
	v_exp_f32_e32 v88, v88
	v_exp_f32_e32 v89, v89
	v_exp_f32_e32 v90, v90
	v_exp_f32_e32 v91, v91
	v_exp_f32_e32 v92, v92
	v_exp_f32_e32 v93, v93
	v_exp_f32_e32 v94, v94
	v_exp_f32_e32 v95, v95
	v_exp_f32_e32 v96, v96
	v_exp_f32_e32 v97, v97
	v_exp_f32_e32 v98, v98
	v_exp_f32_e32 v99, v99
	v_pk_add_f32 v[248:249], v[84:85], v[86:87]
	v_pk_add_f32 v[248:249], v[248:249], v[88:89]
	v_pk_add_f32 v[248:249], v[248:249], v[90:91]
	v_pk_add_f32 v[248:249], v[248:249], v[92:93]
	v_pk_add_f32 v[248:249], v[248:249], v[94:95]
	v_pk_add_f32 v[248:249], v[248:249], v[96:97]
	v_pk_add_f32 v[248:249], v[248:249], v[98:99]
	v_add_f32_e32 v248, v248, v249
	v_cmp_lt_f32_e32 vcc, 0x43800000, v248
	s_cbranch_vccnz .Lbm3_Ag1_redo
	v_cvt_pk_fp8_f32 v84, v84, v85
	v_cvt_pk_fp8_f32 v85, v88, v89
	v_cvt_pk_fp8_f32 v84, v86, v87 op_sel:[0,0,1]
	v_cvt_pk_fp8_f32 v85, v90, v91 op_sel:[0,0,1]
	v_cvt_pk_fp8_f32 v86, v92, v93
	v_cvt_pk_fp8_f32 v87, v96, v97
	v_cvt_pk_fp8_f32 v86, v94, v95 op_sel:[0,0,1]
	v_cvt_pk_fp8_f32 v87, v98, v99 op_sel:[0,0,1]
	v_add_f32_e32 v195, v195, v248
	s_waitcnt vmcnt(8)
	s_nop 1
	v_mfma_f32_16x16x32_fp8_fp8 v[116:119], v[36:37], v[84:85], v[116:119]
	v_mfma_f32_16x16x32_fp8_fp8 v[120:123], v[38:39], v[84:85], v[120:123]
	v_mfma_f32_16x16x32_fp8_fp8 v[124:127], v[40:41], v[84:85], v[124:127]
	v_mfma_f32_16x16x32_fp8_fp8 v[128:131], v[42:43], v[84:85], v[128:131]
	v_mfma_f32_16x16x32_fp8_fp8 v[116:119], v[44:45], v[86:87], v[116:119]
	v_mfma_f32_16x16x32_fp8_fp8 v[120:123], v[46:47], v[86:87], v[120:123]
	v_mfma_f32_16x16x32_fp8_fp8 v[124:127], v[48:49], v[86:87], v[124:127]
	v_mfma_f32_16x16x32_fp8_fp8 v[128:131], v[50:51], v[86:87], v[128:131]
	s_branch .Lbm3_Ag1_skip
.Lbm3_Ag1_redo:
	v_mfma_f32_16x16x32_fp8_fp8 v[84:87], v[2:3], v[168:169], 0
	v_mfma_f32_16x16x32_fp8_fp8 v[88:91], v[6:7], v[168:169], 0
	v_mfma_f32_16x16x32_fp8_fp8 v[92:95], v[12:13], v[168:169], 0
	v_mfma_f32_16x16x32_fp8_fp8 v[96:99], v[16:17], v[168:169], 0
	v_mfma_f32_16x16x32_fp8_fp8 v[84:87], v[4:5], v[170:171], v[84:87]
	v_mfma_f32_16x16x32_fp8_fp8 v[88:91], v[8:9], v[170:171], v[88:91]
	v_mfma_f32_16x16x32_fp8_fp8 v[92:95], v[14:15], v[170:171], v[92:95]
	v_mfma_f32_16x16x32_fp8_fp8 v[96:99], v[18:19], v[170:171], v[96:99]
	s_nop 7
	v_pk_fma_f32 v[84:85], v[84:85], s[10:11], v[200:201] op_sel_hi:[1,1,0]
	v_pk_fma_f32 v[86:87], v[86:87], s[10:11], v[200:201] op_sel_hi:[1,1,0]
	v_pk_fma_f32 v[88:89], v[88:89], s[10:11], v[200:201] op_sel_hi:[1,1,0]
	v_pk_fma_f32 v[90:91], v[90:91], s[10:11], v[200:201] op_sel_hi:[1,1,0]
	v_pk_fma_f32 v[92:93], v[92:93], s[10:11], v[200:201] op_sel_hi:[1,1,0]
	v_pk_fma_f32 v[94:95], v[94:95], s[10:11], v[200:201] op_sel_hi:[1,1,0]
	v_pk_fma_f32 v[96:97], v[96:97], s[10:11], v[200:201] op_sel_hi:[1,1,0]
	v_pk_fma_f32 v[98:99], v[98:99], s[10:11], v[200:201] op_sel_hi:[1,1,0]

.Lbm3_Ag1_skip:
	s_bfe_u32 s29, s48, 0x40008
	s_cmp_eq_u32 s29, 0
	s_cbranch_scc1 .Lbm3_Ag2_skip
	s_waitcnt vmcnt(12)
	v_mfma_f32_16x16x32_fp8_fp8 v[84:87], v[2:3], v[182:183], 0
	v_mfma_f32_16x16x32_fp8_fp8 v[88:91], v[6:7], v[182:183], 0
	v_mfma_f32_16x16x32_fp8_fp8 v[92:95], v[12:13], v[182:183], 0
	v_mfma_f32_16x16x32_fp8_fp8 v[96:99], v[16:17], v[182:183], 0
	v_mfma_f32_16x16x32_fp8_fp8 v[84:87], v[4:5], v[184:185], v[84:87]
	v_mfma_f32_16x16x32_fp8_fp8 v[88:91], v[8:9], v[184:185], v[88:91]
	v_mfma_f32_16x16x32_fp8_fp8 v[92:95], v[14:15], v[184:185], v[92:95]
	v_mfma_f32_16x16x32_fp8_fp8 v[96:99], v[18:19], v[184:185], v[96:99]
	v_and_b32_e32 v199, s29, v244
	s_cmp_eq_u32 s50, 1
	v_cmp_ne_u32_e32 vcc, 0, v199
	s_cbranch_scc1 .Lbm3_Ag2_near
	v_add_f32_e32 v200, v81, v192
	v_cndmask_b32_e32 v200, v77, v200, vcc
	v_pk_fma_f32 v[84:85], v[84:85], s[10:11], v[200:201] op_sel_hi:[1,1,0]
	v_pk_fma_f32 v[86:87], v[86:87], s[10:11], v[200:201] op_sel_hi:[1,1,0]
	v_pk_fma_f32 v[88:89], v[88:89], s[10:11], v[200:201] op_sel_hi:[1,1,0]
	v_pk_fma_f32 v[90:91], v[90:91], s[10:11], v[200:201] op_sel_hi:[1,1,0]
	v_pk_fma_f32 v[92:93], v[92:93], s[10:11], v[200:201] op_sel_hi:[1,1,0]
	v_pk_fma_f32 v[94:95], v[94:95], s[10:11], v[200:201] op_sel_hi:[1,1,0]
	v_pk_fma_f32 v[96:97], v[96:97], s[10:11], v[200:201] op_sel_hi:[1,1,0]
	v_pk_fma_f32 v[98:99], v[98:99], s[10:11], v[200:201] op_sel_hi:[1,1,0]
	s_cmp_eq_u32 s35, 0
	s_cbranch_scc1 .Lbm3_Ag2_max
	v_exp_f32_e32 v84, v84
	v_exp_f32_e32 v85, v85
	v_exp_f32_e32 v86, v86
	v_exp_f32_e32 v87, v87
	v_exp_f32_e32 v88, v88
	v_exp_f32_e32 v89, v89
	v_exp_f32_e32 v90, v90
	v_exp_f32_e32 v91, v91
	v_exp_f32_e32 v92, v92
	v_exp_f32_e32 v93, v93
	v_exp_f32_e32 v94, v94
	v_exp_f32_e32 v95, v95
	v_exp_f32_e32 v96, v96
	v_exp_f32_e32 v97, v97
	v_exp_f32_e32 v98, v98
	v_exp_f32_e32 v99, v99
	v_pk_add_f32 v[248:249], v[84:85], v[86:87]
	v_pk_add_f32 v[248:249], v[248:249], v[88:89]
	v_pk_add_f32 v[248:249], v[248:249], v[90:91]
	v_pk_add_f32 v[248:249], v[248:249], v[92:93]
	v_pk_add_f32 v[248:249], v[248:249], v[94:95]
	v_pk_add_f32 v[248:249], v[248:249], v[96:97]
	v_pk_add_f32 v[248:249], v[248:249], v[98:99]
	v_add_f32_e32 v248, v248, v249
	v_cmp_lt_f32_e32 vcc, 0x43800000, v248
	s_cbranch_vccnz .Lbm3_Ag2_redo
	v_cvt_pk_fp8_f32 v84, v84, v85
	v_cvt_pk_fp8_f32 v85, v88, v89
	v_cvt_pk_fp8_f32 v84, v86, v87 op_sel:[0,0,1]
	v_cvt_pk_fp8_f32 v85, v90, v91 op_sel:[0,0,1]
	v_cvt_pk_fp8_f32 v86, v92, v93
	v_cvt_pk_fp8_f32 v87, v96, v97
	v_cvt_pk_fp8_f32 v86, v94, v95 op_sel:[0,0,1]
	v_cvt_pk_fp8_f32 v87, v98, v99 op_sel:[0,0,1]
	v_add_f32_e32 v196, v196, v248
	s_waitcnt vmcnt(8)
	s_nop 1
	v_mfma_f32_16x16x32_fp8_fp8 v[132:135], v[36:37], v[84:85], v[132:135]
	v_mfma_f32_16x16x32_fp8_fp8 v[136:139], v[38:39], v[84:85], v[136:139]
	v_mfma_f32_16x16x32_fp8_fp8 v[140:143], v[40:41], v[84:85], v[140:143]
	v_mfma_f32_16x16x32_fp8_fp8 v[144:147], v[42:43], v[84:85], v[144:147]
	v_mfma_f32_16x16x32_fp8_fp8 v[132:135], v[44:45], v[86:87], v[132:135]
	v_mfma_f32_16x16x32_fp8_fp8 v[136:139], v[46:47], v[86:87], v[136:139]
	v_mfma_f32_16x16x32_fp8_fp8 v[140:143], v[48:49], v[86:87], v[140:143]
	v_mfma_f32_16x16x32_fp8_fp8 v[144:147], v[50:51], v[86:87], v[144:147]
	s_branch .Lbm3_Ag2_skip
.Lbm3_Ag2_redo:
	v_mfma_f32_16x16x32_fp8_fp8 v[84:87], v[2:3], v[182:183], 0
	v_mfma_f32_16x16x32_fp8_fp8 v[88:91], v[6:7], v[182:183], 0
	v_mfma_f32_16x16x32_fp8_fp8 v[92:95], v[12:13], v[182:183], 0
	v_mfma_f32_16x16x32_fp8_fp8 v[96:99], v[16:17], v[182:183], 0
	v_mfma_f32_16x16x32_fp8_fp8 v[84:87], v[4:5], v[184:185], v[84:87]
	v_mfma_f32_16x16x32_fp8_fp8 v[88:91], v[8:9], v[184:185], v[88:91]
	v_mfma_f32_16x16x32_fp8_fp8 v[92:95], v[14:15], v[184:185], v[92:95]
	v_mfma_f32_16x16x32_fp8_fp8 v[96:99], v[18:19], v[184:185], v[96:99]
	s_nop 7
	v_pk_fma_f32 v[84:85], v[84:85], s[10:11], v[200:201] op_sel_hi:[1,1,0]
	v_pk_fma_f32 v[86:87], v[86:87], s[10:11], v[200:201] op_sel_hi:[1,1,0]
	v_pk_fma_f32 v[88:89], v[88:89], s[10:11], v[200:201] op_sel_hi:[1,1,0]
	v_pk_fma_f32 v[90:91], v[90:91], s[10:11], v[200:201] op_sel_hi:[1,1,0]
	v_pk_fma_f32 v[92:93], v[92:93], s[10:11], v[200:201] op_sel_hi:[1,1,0]
	v_pk_fma_f32 v[94:95], v[94:95], s[10:11], v[200:201] op_sel_hi:[1,1,0]
	v_pk_fma_f32 v[96:97], v[96:97], s[10:11], v[200:201] op_sel_hi:[1,1,0]
	v_pk_fma_f32 v[98:99], v[98:99], s[10:11], v[200:201] op_sel_hi:[1,1,0]

.Lbm3_Ag2_skip:
	s_bfe_u32 s29, s48, 0x4000c
	s_cmp_eq_u32 s29, 0
	s_cbranch_scc1 .Lbm3_Ag3_skip
	s_waitcnt vmcnt(12)
	v_mfma_f32_16x16x32_fp8_fp8 v[84:87], v[2:3], v[186:187], 0
	v_mfma_f32_16x16x32_fp8_fp8 v[88:91], v[6:7], v[186:187], 0
	v_mfma_f32_16x16x32_fp8_fp8 v[92:95], v[12:13], v[186:187], 0
	v_mfma_f32_16x16x32_fp8_fp8 v[96:99], v[16:17], v[186:187], 0
	v_mfma_f32_16x16x32_fp8_fp8 v[84:87], v[4:5], v[188:189], v[84:87]
	v_mfma_f32_16x16x32_fp8_fp8 v[88:91], v[8:9], v[188:189], v[88:91]
	v_mfma_f32_16x16x32_fp8_fp8 v[92:95], v[14:15], v[188:189], v[92:95]
	v_mfma_f32_16x16x32_fp8_fp8 v[96:99], v[18:19], v[188:189], v[96:99]
	v_and_b32_e32 v199, s29, v244
	s_cmp_eq_u32 s50, 1
	v_cmp_ne_u32_e32 vcc, 0, v199
	s_cbranch_scc1 .Lbm3_Ag3_near
	v_add_f32_e32 v200, v81, v193
	v_cndmask_b32_e32 v200, v77, v200, vcc
	v_pk_fma_f32 v[84:85], v[84:85], s[10:11], v[200:201] op_sel_hi:[1,1,0]
	v_pk_fma_f32 v[86:87], v[86:87], s[10:11], v[200:201] op_sel_hi:[1,1,0]
	v_pk_fma_f32 v[88:89], v[88:89], s[10:11], v[200:201] op_sel_hi:[1,1,0]
	v_pk_fma_f32 v[90:91], v[90:91], s[10:11], v[200:201] op_sel_hi:[1,1,0]
	v_pk_fma_f32 v[92:93], v[92:93], s[10:11], v[200:201] op_sel_hi:[1,1,0]
	v_pk_fma_f32 v[94:95], v[94:95], s[10:11], v[200:201] op_sel_hi:[1,1,0]
	v_pk_fma_f32 v[96:97], v[96:97], s[10:11], v[200:201] op_sel_hi:[1,1,0]
	v_pk_fma_f32 v[98:99], v[98:99], s[10:11], v[200:201] op_sel_hi:[1,1,0]
	s_cmp_eq_u32 s35, 0
	s_cbranch_scc1 .Lbm3_Ag3_max
	v_exp_f32_e32 v84, v84
	v_exp_f32_e32 v85, v85
	v_exp_f32_e32 v86, v86
	v_exp_f32_e32 v87, v87
	v_exp_f32_e32 v88, v88
	v_exp_f32_e32 v89, v89
	v_exp_f32_e32 v90, v90
	v_exp_f32_e32 v91, v91
	v_exp_f32_e32 v92, v92
	v_exp_f32_e32 v93, v93
	v_exp_f32_e32 v94, v94
	v_exp_f32_e32 v95, v95
	v_exp_f32_e32 v96, v96
	v_exp_f32_e32 v97, v97
	v_exp_f32_e32 v98, v98
	v_exp_f32_e32 v99, v99
	v_pk_add_f32 v[248:249], v[84:85], v[86:87]
	v_pk_add_f32 v[248:249], v[248:249], v[88:89]
	v_pk_add_f32 v[248:249], v[248:249], v[90:91]
	v_pk_add_f32 v[248:249], v[248:249], v[92:93]
	v_pk_add_f32 v[248:249], v[248:249], v[94:95]
	v_pk_add_f32 v[248:249], v[248:249], v[96:97]
	v_pk_add_f32 v[248:249], v[248:249], v[98:99]
	v_add_f32_e32 v248, v248, v249
	v_cmp_lt_f32_e32 vcc, 0x43800000, v248
	s_cbranch_vccnz .Lbm3_Ag3_redo
	v_cvt_pk_fp8_f32 v84, v84, v85
	v_cvt_pk_fp8_f32 v85, v88, v89
	v_cvt_pk_fp8_f32 v84, v86, v87 op_sel:[0,0,1]
	v_cvt_pk_fp8_f32 v85, v90, v91 op_sel:[0,0,1]
	v_cvt_pk_fp8_f32 v86, v92, v93
	v_cvt_pk_fp8_f32 v87, v96, v97
	v_cvt_pk_fp8_f32 v86, v94, v95 op_sel:[0,0,1]
	v_cvt_pk_fp8_f32 v87, v98, v99 op_sel:[0,0,1]
	v_add_f32_e32 v197, v197, v248
	s_waitcnt vmcnt(8)
	s_nop 1
	v_mfma_f32_16x16x32_fp8_fp8 v[148:151], v[36:37], v[84:85], v[148:151]
	v_mfma_f32_16x16x32_fp8_fp8 v[152:155], v[38:39], v[84:85], v[152:155]
	v_mfma_f32_16x16x32_fp8_fp8 v[156:159], v[40:41], v[84:85], v[156:159]
	v_mfma_f32_16x16x32_fp8_fp8 v[160:163], v[42:43], v[84:85], v[160:163]
	v_mfma_f32_16x16x32_fp8_fp8 v[148:151], v[44:45], v[86:87], v[148:151]
	v_mfma_f32_16x16x32_fp8_fp8 v[152:155], v[46:47], v[86:87], v[152:155]
	v_mfma_f32_16x16x32_fp8_fp8 v[156:159], v[48:49], v[86:87], v[156:159]
	v_mfma_f32_16x16x32_fp8_fp8 v[160:163], v[50:51], v[86:87], v[160:163]
	s_branch .Lbm3_Ag3_skip
.Lbm3_Ag3_redo:
	v_mfma_f32_16x16x32_fp8_fp8 v[84:87], v[2:3], v[186:187], 0
	v_mfma_f32_16x16x32_fp8_fp8 v[88:91], v[6:7], v[186:187], 0
	v_mfma_f32_16x16x32_fp8_fp8 v[92:95], v[12:13], v[186:187], 0
	v_mfma_f32_16x16x32_fp8_fp8 v[96:99], v[16:17], v[186:187], 0
	v_mfma_f32_16x16x32_fp8_fp8 v[84:87], v[4:5], v[188:189], v[84:87]
	v_mfma_f32_16x16x32_fp8_fp8 v[88:91], v[8:9], v[188:189], v[88:91]
	v_mfma_f32_16x16x32_fp8_fp8 v[92:95], v[14:15], v[188:189], v[92:95]
	v_mfma_f32_16x16x32_fp8_fp8 v[96:99], v[18:19], v[188:189], v[96:99]
	s_nop 7
	v_pk_fma_f32 v[84:85], v[84:85], s[10:11], v[200:201] op_sel_hi:[1,1,0]
	v_pk_fma_f32 v[86:87], v[86:87], s[10:11], v[200:201] op_sel_hi:[1,1,0]
	v_pk_fma_f32 v[88:89], v[88:89], s[10:11], v[200:201] op_sel_hi:[1,1,0]
	v_pk_fma_f32 v[90:91], v[90:91], s[10:11], v[200:201] op_sel_hi:[1,1,0]
	v_pk_fma_f32 v[92:93], v[92:93], s[10:11], v[200:201] op_sel_hi:[1,1,0]
	v_pk_fma_f32 v[94:95], v[94:95], s[10:11], v[200:201] op_sel_hi:[1,1,0]
	v_pk_fma_f32 v[96:97], v[96:97], s[10:11], v[200:201] op_sel_hi:[1,1,0]
	v_pk_fma_f32 v[98:99], v[98:99], s[10:11], v[200:201] op_sel_hi:[1,1,0]

.Lbm3_blkB:
	s_lshl_b32 s29, s27, 12
	s_add_u32 s30, s40, s29
	s_addc_u32 s31, s41, 0
	global_load_dwordx4 v[2:5], v79, s[30:31]
	global_load_dwordx4 v[6:9], v79, s[30:31] offset:1024
	global_load_dwordx4 v[12:15], v79, s[30:31] offset:2048
	global_load_dwordx4 v[16:19], v79, s[30:31] offset:3072
	s_lshl_b32 s29, s27, 12
	s_add_u32 s30, s62, s29
	s_addc_u32 s31, s63, 0
	global_load_dwordx4 v[36:39], v79, s[30:31]
	global_load_dwordx4 v[40:43], v79, s[30:31] offset:1024
	global_load_dwordx4 v[44:47], v79, s[30:31] offset:2048
	global_load_dwordx4 v[48:51], v79, s[30:31] offset:3072
	s_add_i32 s50, s35, 2
	s_add_i32 s9, s25, -1
	s_min_i32 s50, s50, s9
	s_lshl_b32 s9, s50, 2
	s_add_i32 s9, s9, s46
	v_mov_b32_e32 v76, s9
	ds_read_b32 v76, v76 offset:16384
	s_cmp_ge_i32 s38, s21
	s_cselect_b32 s50, 1, 0
	s_bfe_u32 s29, s48, 0x40000
	s_cmp_eq_u32 s29, 0
	s_cbranch_scc1 .Lbm3_Bg0_skip
	s_waitcnt vmcnt(12)
	v_mfma_f32_16x16x32_fp8_fp8 v[84:87], v[20:21], v[164:165], 0
	v_mfma_f32_16x16x32_fp8_fp8 v[88:91], v[24:25], v[164:165], 0
	v_mfma_f32_16x16x32_fp8_fp8 v[92:95], v[28:29], v[164:165], 0
	v_mfma_f32_16x16x32_fp8_fp8 v[96:99], v[32:33], v[164:165], 0
	v_mfma_f32_16x16x32_fp8_fp8 v[84:87], v[22:23], v[166:167], v[84:87]
	v_mfma_f32_16x16x32_fp8_fp8 v[88:91], v[26:27], v[166:167], v[88:91]
	v_mfma_f32_16x16x32_fp8_fp8 v[92:95], v[30:31], v[166:167], v[92:95]
	v_mfma_f32_16x16x32_fp8_fp8 v[96:99], v[34:35], v[166:167], v[96:99]
	v_and_b32_e32 v199, s29, v244
	s_cmp_eq_u32 s50, 1
	v_cmp_ne_u32_e32 vcc, 0, v199
	s_cbranch_scc1 .Lbm3_Bg0_near
	v_add_f32_e32 v200, v81, v190
	v_cndmask_b32_e32 v200, v77, v200, vcc
	v_pk_fma_f32 v[84:85], v[84:85], s[10:11], v[200:201] op_sel_hi:[1,1,0]
	v_pk_fma_f32 v[86:87], v[86:87], s[10:11], v[200:201] op_sel_hi:[1,1,0]
	v_pk_fma_f32 v[88:89], v[88:89], s[10:11], v[200:201] op_sel_hi:[1,1,0]
	v_pk_fma_f32 v[90:91], v[90:91], s[10:11], v[200:201] op_sel_hi:[1,1,0]
	v_pk_fma_f32 v[92:93], v[92:93], s[10:11], v[200:201] op_sel_hi:[1,1,0]
	v_pk_fma_f32 v[94:95], v[94:95], s[10:11], v[200:201] op_sel_hi:[1,1,0]
	v_pk_fma_f32 v[96:97], v[96:97], s[10:11], v[200:201] op_sel_hi:[1,1,0]
	v_pk_fma_f32 v[98:99], v[98:99], s[10:11], v[200:201] op_sel_hi:[1,1,0]
	s_cmp_eq_u32 s35, 0
	s_cbranch_scc1 .Lbm3_Bg0_max
	v_exp_f32_e32 v84, v84
	v_exp_f32_e32 v85, v85
	v_exp_f32_e32 v86, v86
	v_exp_f32_e32 v87, v87
	v_exp_f32_e32 v88, v88
	v_exp_f32_e32 v89, v89
	v_exp_f32_e32 v90, v90
	v_exp_f32_e32 v91, v91
	v_exp_f32_e32 v92, v92
	v_exp_f32_e32 v93, v93
	v_exp_f32_e32 v94, v94
	v_exp_f32_e32 v95, v95
	v_exp_f32_e32 v96, v96
	v_exp_f32_e32 v97, v97
	v_exp_f32_e32 v98, v98
	v_exp_f32_e32 v99, v99
	v_pk_add_f32 v[248:249], v[84:85], v[86:87]
	v_pk_add_f32 v[248:249], v[248:249], v[88:89]
	v_pk_add_f32 v[248:249], v[248:249], v[90:91]
	v_pk_add_f32 v[248:249], v[248:249], v[92:93]
	v_pk_add_f32 v[248:249], v[248:249], v[94:95]
	v_pk_add_f32 v[248:249], v[248:249], v[96:97]
	v_pk_add_f32 v[248:249], v[248:249], v[98:99]
	v_add_f32_e32 v248, v248, v249
	v_cmp_lt_f32_e32 vcc, 0x43800000, v248
	s_cbranch_vccnz .Lbm3_Bg0_redo
	v_cvt_pk_fp8_f32 v84, v84, v85
	v_cvt_pk_fp8_f32 v85, v88, v89
	v_cvt_pk_fp8_f32 v84, v86, v87 op_sel:[0,0,1]
	v_cvt_pk_fp8_f32 v85, v90, v91 op_sel:[0,0,1]
	v_cvt_pk_fp8_f32 v86, v92, v93
	v_cvt_pk_fp8_f32 v87, v96, v97
	v_cvt_pk_fp8_f32 v86, v94, v95 op_sel:[0,0,1]
	v_cvt_pk_fp8_f32 v87, v98, v99 op_sel:[0,0,1]
	v_add_f32_e32 v194, v194, v248
	s_waitcnt vmcnt(8)
	s_nop 1
	v_mfma_f32_16x16x32_fp8_fp8 v[100:103], v[52:53], v[84:85], v[100:103]
	v_mfma_f32_16x16x32_fp8_fp8 v[104:107], v[54:55], v[84:85], v[104:107]
	v_mfma_f32_16x16x32_fp8_fp8 v[108:111], v[56:57], v[84:85], v[108:111]
	v_mfma_f32_16x16x32_fp8_fp8 v[112:115], v[58:59], v[84:85], v[112:115]
	v_mfma_f32_16x16x32_fp8_fp8 v[100:103], v[60:61], v[86:87], v[100:103]
	v_mfma_f32_16x16x32_fp8_fp8 v[104:107], v[62:63], v[86:87], v[104:107]
	v_mfma_f32_16x16x32_fp8_fp8 v[108:111], v[64:65], v[86:87], v[108:111]
	v_mfma_f32_16x16x32_fp8_fp8 v[112:115], v[66:67], v[86:87], v[112:115]
	s_branch .Lbm3_Bg0_skip
.Lbm3_Bg0_redo:
	v_mfma_f32_16x16x32_fp8_fp8 v[84:87], v[20:21], v[164:165], 0
	v_mfma_f32_16x16x32_fp8_fp8 v[88:91], v[24:25], v[164:165], 0
	v_mfma_f32_16x16x32_fp8_fp8 v[92:95], v[28:29], v[164:165], 0
	v_mfma_f32_16x16x32_fp8_fp8 v[96:99], v[32:33], v[164:165], 0
	v_mfma_f32_16x16x32_fp8_fp8 v[84:87], v[22:23], v[166:167], v[84:87]
	v_mfma_f32_16x16x32_fp8_fp8 v[88:91], v[26:27], v[166:167], v[88:91]
	v_mfma_f32_16x16x32_fp8_fp8 v[92:95], v[30:31], v[166:167], v[92:95]
	v_mfma_f32_16x16x32_fp8_fp8 v[96:99], v[34:35], v[166:167], v[96:99]
	s_nop 7
	v_pk_fma_f32 v[84:85], v[84:85], s[10:11], v[200:201] op_sel_hi:[1,1,0]
	v_pk_fma_f32 v[86:87], v[86:87], s[10:11], v[200:201] op_sel_hi:[1,1,0]
	v_pk_fma_f32 v[88:89], v[88:89], s[10:11], v[200:201] op_sel_hi:[1,1,0]
	v_pk_fma_f32 v[90:91], v[90:91], s[10:11], v[200:201] op_sel_hi:[1,1,0]
	v_pk_fma_f32 v[92:93], v[92:93], s[10:11], v[200:201] op_sel_hi:[1,1,0]
	v_pk_fma_f32 v[94:95], v[94:95], s[10:11], v[200:201] op_sel_hi:[1,1,0]
	v_pk_fma_f32 v[96:97], v[96:97], s[10:11], v[200:201] op_sel_hi:[1,1,0]
	v_pk_fma_f32 v[98:99], v[98:99], s[10:11], v[200:201] op_sel_hi:[1,1,0]

.Lbm3_Bg0_skip:
	s_bfe_u32 s29, s48, 0x40004
	s_cmp_eq_u32 s29, 0
	s_cbranch_scc1 .Lbm3_Bg1_skip
	s_waitcnt vmcnt(12)
	v_mfma_f32_16x16x32_fp8_fp8 v[84:87], v[20:21], v[168:169], 0
	v_mfma_f32_16x16x32_fp8_fp8 v[88:91], v[24:25], v[168:169], 0
	v_mfma_f32_16x16x32_fp8_fp8 v[92:95], v[28:29], v[168:169], 0
	v_mfma_f32_16x16x32_fp8_fp8 v[96:99], v[32:33], v[168:169], 0
	v_mfma_f32_16x16x32_fp8_fp8 v[84:87], v[22:23], v[170:171], v[84:87]
	v_mfma_f32_16x16x32_fp8_fp8 v[88:91], v[26:27], v[170:171], v[88:91]
	v_mfma_f32_16x16x32_fp8_fp8 v[92:95], v[30:31], v[170:171], v[92:95]
	v_mfma_f32_16x16x32_fp8_fp8 v[96:99], v[34:35], v[170:171], v[96:99]
	v_and_b32_e32 v199, s29, v244
	s_cmp_eq_u32 s50, 1
	v_cmp_ne_u32_e32 vcc, 0, v199
	s_cbranch_scc1 .Lbm3_Bg1_near
	v_add_f32_e32 v200, v81, v191
	v_cndmask_b32_e32 v200, v77, v200, vcc
	v_pk_fma_f32 v[84:85], v[84:85], s[10:11], v[200:201] op_sel_hi:[1,1,0]
	v_pk_fma_f32 v[86:87], v[86:87], s[10:11], v[200:201] op_sel_hi:[1,1,0]
	v_pk_fma_f32 v[88:89], v[88:89], s[10:11], v[200:201] op_sel_hi:[1,1,0]
	v_pk_fma_f32 v[90:91], v[90:91], s[10:11], v[200:201] op_sel_hi:[1,1,0]
	v_pk_fma_f32 v[92:93], v[92:93], s[10:11], v[200:201] op_sel_hi:[1,1,0]
	v_pk_fma_f32 v[94:95], v[94:95], s[10:11], v[200:201] op_sel_hi:[1,1,0]
	v_pk_fma_f32 v[96:97], v[96:97], s[10:11], v[200:201] op_sel_hi:[1,1,0]
	v_pk_fma_f32 v[98:99], v[98:99], s[10:11], v[200:201] op_sel_hi:[1,1,0]
	s_cmp_eq_u32 s35, 0
	s_cbranch_scc1 .Lbm3_Bg1_max
	v_exp_f32_e32 v84, v84
	v_exp_f32_e32 v85, v85
	v_exp_f32_e32 v86, v86
	v_exp_f32_e32 v87, v87
	v_exp_f32_e32 v88, v88
	v_exp_f32_e32 v89, v89
	v_exp_f32_e32 v90, v90
	v_exp_f32_e32 v91, v91
	v_exp_f32_e32 v92, v92
	v_exp_f32_e32 v93, v93
	v_exp_f32_e32 v94, v94
	v_exp_f32_e32 v95, v95
	v_exp_f32_e32 v96, v96
	v_exp_f32_e32 v97, v97
	v_exp_f32_e32 v98, v98
	v_exp_f32_e32 v99, v99
	v_pk_add_f32 v[248:249], v[84:85], v[86:87]
	v_pk_add_f32 v[248:249], v[248:249], v[88:89]
	v_pk_add_f32 v[248:249], v[248:249], v[90:91]
	v_pk_add_f32 v[248:249], v[248:249], v[92:93]
	v_pk_add_f32 v[248:249], v[248:249], v[94:95]
	v_pk_add_f32 v[248:249], v[248:249], v[96:97]
	v_pk_add_f32 v[248:249], v[248:249], v[98:99]
	v_add_f32_e32 v248, v248, v249
	v_cmp_lt_f32_e32 vcc, 0x43800000, v248
	s_cbranch_vccnz .Lbm3_Bg1_redo
	v_cvt_pk_fp8_f32 v84, v84, v85
	v_cvt_pk_fp8_f32 v85, v88, v89
	v_cvt_pk_fp8_f32 v84, v86, v87 op_sel:[0,0,1]
	v_cvt_pk_fp8_f32 v85, v90, v91 op_sel:[0,0,1]
	v_cvt_pk_fp8_f32 v86, v92, v93
	v_cvt_pk_fp8_f32 v87, v96, v97
	v_cvt_pk_fp8_f32 v86, v94, v95 op_sel:[0,0,1]
	v_cvt_pk_fp8_f32 v87, v98, v99 op_sel:[0,0,1]
	v_add_f32_e32 v195, v195, v248
	s_waitcnt vmcnt(8)
	s_nop 1
	v_mfma_f32_16x16x32_fp8_fp8 v[116:119], v[52:53], v[84:85], v[116:119]
	v_mfma_f32_16x16x32_fp8_fp8 v[120:123], v[54:55], v[84:85], v[120:123]
	v_mfma_f32_16x16x32_fp8_fp8 v[124:127], v[56:57], v[84:85], v[124:127]
	v_mfma_f32_16x16x32_fp8_fp8 v[128:131], v[58:59], v[84:85], v[128:131]
	v_mfma_f32_16x16x32_fp8_fp8 v[116:119], v[60:61], v[86:87], v[116:119]
	v_mfma_f32_16x16x32_fp8_fp8 v[120:123], v[62:63], v[86:87], v[120:123]
	v_mfma_f32_16x16x32_fp8_fp8 v[124:127], v[64:65], v[86:87], v[124:127]
	v_mfma_f32_16x16x32_fp8_fp8 v[128:131], v[66:67], v[86:87], v[128:131]
	s_branch .Lbm3_Bg1_skip
.Lbm3_Bg1_redo:
	v_mfma_f32_16x16x32_fp8_fp8 v[84:87], v[20:21], v[168:169], 0
	v_mfma_f32_16x16x32_fp8_fp8 v[88:91], v[24:25], v[168:169], 0
	v_mfma_f32_16x16x32_fp8_fp8 v[92:95], v[28:29], v[168:169], 0
	v_mfma_f32_16x16x32_fp8_fp8 v[96:99], v[32:33], v[168:169], 0
	v_mfma_f32_16x16x32_fp8_fp8 v[84:87], v[22:23], v[170:171], v[84:87]
	v_mfma_f32_16x16x32_fp8_fp8 v[88:91], v[26:27], v[170:171], v[88:91]
	v_mfma_f32_16x16x32_fp8_fp8 v[92:95], v[30:31], v[170:171], v[92:95]
	v_mfma_f32_16x16x32_fp8_fp8 v[96:99], v[34:35], v[170:171], v[96:99]
	s_nop 7
	v_pk_fma_f32 v[84:85], v[84:85], s[10:11], v[200:201] op_sel_hi:[1,1,0]
	v_pk_fma_f32 v[86:87], v[86:87], s[10:11], v[200:201] op_sel_hi:[1,1,0]
	v_pk_fma_f32 v[88:89], v[88:89], s[10:11], v[200:201] op_sel_hi:[1,1,0]
	v_pk_fma_f32 v[90:91], v[90:91], s[10:11], v[200:201] op_sel_hi:[1,1,0]
	v_pk_fma_f32 v[92:93], v[92:93], s[10:11], v[200:201] op_sel_hi:[1,1,0]
	v_pk_fma_f32 v[94:95], v[94:95], s[10:11], v[200:201] op_sel_hi:[1,1,0]
	v_pk_fma_f32 v[96:97], v[96:97], s[10:11], v[200:201] op_sel_hi:[1,1,0]
	v_pk_fma_f32 v[98:99], v[98:99], s[10:11], v[200:201] op_sel_hi:[1,1,0]

.Lbm3_Bg1_skip:
	s_bfe_u32 s29, s48, 0x40008
	s_cmp_eq_u32 s29, 0
	s_cbranch_scc1 .Lbm3_Bg2_skip
	s_waitcnt vmcnt(12)
	v_mfma_f32_16x16x32_fp8_fp8 v[84:87], v[20:21], v[182:183], 0
	v_mfma_f32_16x16x32_fp8_fp8 v[88:91], v[24:25], v[182:183], 0
	v_mfma_f32_16x16x32_fp8_fp8 v[92:95], v[28:29], v[182:183], 0
	v_mfma_f32_16x16x32_fp8_fp8 v[96:99], v[32:33], v[182:183], 0
	v_mfma_f32_16x16x32_fp8_fp8 v[84:87], v[22:23], v[184:185], v[84:87]
	v_mfma_f32_16x16x32_fp8_fp8 v[88:91], v[26:27], v[184:185], v[88:91]
	v_mfma_f32_16x16x32_fp8_fp8 v[92:95], v[30:31], v[184:185], v[92:95]
	v_mfma_f32_16x16x32_fp8_fp8 v[96:99], v[34:35], v[184:185], v[96:99]
	v_and_b32_e32 v199, s29, v244
	s_cmp_eq_u32 s50, 1
	v_cmp_ne_u32_e32 vcc, 0, v199
	s_cbranch_scc1 .Lbm3_Bg2_near
	v_add_f32_e32 v200, v81, v192
	v_cndmask_b32_e32 v200, v77, v200, vcc
	v_pk_fma_f32 v[84:85], v[84:85], s[10:11], v[200:201] op_sel_hi:[1,1,0]
	v_pk_fma_f32 v[86:87], v[86:87], s[10:11], v[200:201] op_sel_hi:[1,1,0]
	v_pk_fma_f32 v[88:89], v[88:89], s[10:11], v[200:201] op_sel_hi:[1,1,0]
	v_pk_fma_f32 v[90:91], v[90:91], s[10:11], v[200:201] op_sel_hi:[1,1,0]
	v_pk_fma_f32 v[92:93], v[92:93], s[10:11], v[200:201] op_sel_hi:[1,1,0]
	v_pk_fma_f32 v[94:95], v[94:95], s[10:11], v[200:201] op_sel_hi:[1,1,0]
	v_pk_fma_f32 v[96:97], v[96:97], s[10:11], v[200:201] op_sel_hi:[1,1,0]
	v_pk_fma_f32 v[98:99], v[98:99], s[10:11], v[200:201] op_sel_hi:[1,1,0]
	s_cmp_eq_u32 s35, 0
	s_cbranch_scc1 .Lbm3_Bg2_max
	v_exp_f32_e32 v84, v84
	v_exp_f32_e32 v85, v85
	v_exp_f32_e32 v86, v86
	v_exp_f32_e32 v87, v87
	v_exp_f32_e32 v88, v88
	v_exp_f32_e32 v89, v89
	v_exp_f32_e32 v90, v90
	v_exp_f32_e32 v91, v91
	v_exp_f32_e32 v92, v92
	v_exp_f32_e32 v93, v93
	v_exp_f32_e32 v94, v94
	v_exp_f32_e32 v95, v95
	v_exp_f32_e32 v96, v96
	v_exp_f32_e32 v97, v97
	v_exp_f32_e32 v98, v98
	v_exp_f32_e32 v99, v99
	v_pk_add_f32 v[248:249], v[84:85], v[86:87]
	v_pk_add_f32 v[248:249], v[248:249], v[88:89]
	v_pk_add_f32 v[248:249], v[248:249], v[90:91]
	v_pk_add_f32 v[248:249], v[248:249], v[92:93]
	v_pk_add_f32 v[248:249], v[248:249], v[94:95]
	v_pk_add_f32 v[248:249], v[248:249], v[96:97]
	v_pk_add_f32 v[248:249], v[248:249], v[98:99]
	v_add_f32_e32 v248, v248, v249
	v_cmp_lt_f32_e32 vcc, 0x43800000, v248
	s_cbranch_vccnz .Lbm3_Bg2_redo
	v_cvt_pk_fp8_f32 v84, v84, v85
	v_cvt_pk_fp8_f32 v85, v88, v89
	v_cvt_pk_fp8_f32 v84, v86, v87 op_sel:[0,0,1]
	v_cvt_pk_fp8_f32 v85, v90, v91 op_sel:[0,0,1]
	v_cvt_pk_fp8_f32 v86, v92, v93
	v_cvt_pk_fp8_f32 v87, v96, v97
	v_cvt_pk_fp8_f32 v86, v94, v95 op_sel:[0,0,1]
	v_cvt_pk_fp8_f32 v87, v98, v99 op_sel:[0,0,1]
	v_add_f32_e32 v196, v196, v248
	s_waitcnt vmcnt(8)
	s_nop 1
	v_mfma_f32_16x16x32_fp8_fp8 v[132:135], v[52:53], v[84:85], v[132:135]
	v_mfma_f32_16x16x32_fp8_fp8 v[136:139], v[54:55], v[84:85], v[136:139]
	v_mfma_f32_16x16x32_fp8_fp8 v[140:143], v[56:57], v[84:85], v[140:143]
	v_mfma_f32_16x16x32_fp8_fp8 v[144:147], v[58:59], v[84:85], v[144:147]
	v_mfma_f32_16x16x32_fp8_fp8 v[132:135], v[60:61], v[86:87], v[132:135]
	v_mfma_f32_16x16x32_fp8_fp8 v[136:139], v[62:63], v[86:87], v[136:139]
	v_mfma_f32_16x16x32_fp8_fp8 v[140:143], v[64:65], v[86:87], v[140:143]
	v_mfma_f32_16x16x32_fp8_fp8 v[144:147], v[66:67], v[86:87], v[144:147]
	s_branch .Lbm3_Bg2_skip
.Lbm3_Bg2_redo:
	v_mfma_f32_16x16x32_fp8_fp8 v[84:87], v[20:21], v[182:183], 0
	v_mfma_f32_16x16x32_fp8_fp8 v[88:91], v[24:25], v[182:183], 0
	v_mfma_f32_16x16x32_fp8_fp8 v[92:95], v[28:29], v[182:183], 0
	v_mfma_f32_16x16x32_fp8_fp8 v[96:99], v[32:33], v[182:183], 0
	v_mfma_f32_16x16x32_fp8_fp8 v[84:87], v[22:23], v[184:185], v[84:87]
	v_mfma_f32_16x16x32_fp8_fp8 v[88:91], v[26:27], v[184:185], v[88:91]
	v_mfma_f32_16x16x32_fp8_fp8 v[92:95], v[30:31], v[184:185], v[92:95]
	v_mfma_f32_16x16x32_fp8_fp8 v[96:99], v[34:35], v[184:185], v[96:99]
	s_nop 7
	v_pk_fma_f32 v[84:85], v[84:85], s[10:11], v[200:201] op_sel_hi:[1,1,0]
	v_pk_fma_f32 v[86:87], v[86:87], s[10:11], v[200:201] op_sel_hi:[1,1,0]
	v_pk_fma_f32 v[88:89], v[88:89], s[10:11], v[200:201] op_sel_hi:[1,1,0]
	v_pk_fma_f32 v[90:91], v[90:91], s[10:11], v[200:201] op_sel_hi:[1,1,0]
	v_pk_fma_f32 v[92:93], v[92:93], s[10:11], v[200:201] op_sel_hi:[1,1,0]
	v_pk_fma_f32 v[94:95], v[94:95], s[10:11], v[200:201] op_sel_hi:[1,1,0]
	v_pk_fma_f32 v[96:97], v[96:97], s[10:11], v[200:201] op_sel_hi:[1,1,0]
	v_pk_fma_f32 v[98:99], v[98:99], s[10:11], v[200:201] op_sel_hi:[1,1,0]

.Lbm3_Bg2_skip:
	s_bfe_u32 s29, s48, 0x4000c
	s_cmp_eq_u32 s29, 0
	s_cbranch_scc1 .Lbm3_Bg3_skip
	s_waitcnt vmcnt(12)
	v_mfma_f32_16x16x32_fp8_fp8 v[84:87], v[20:21], v[186:187], 0
	v_mfma_f32_16x16x32_fp8_fp8 v[88:91], v[24:25], v[186:187], 0
	v_mfma_f32_16x16x32_fp8_fp8 v[92:95], v[28:29], v[186:187], 0
	v_mfma_f32_16x16x32_fp8_fp8 v[96:99], v[32:33], v[186:187], 0
	v_mfma_f32_16x16x32_fp8_fp8 v[84:87], v[22:23], v[188:189], v[84:87]
	v_mfma_f32_16x16x32_fp8_fp8 v[88:91], v[26:27], v[188:189], v[88:91]
	v_mfma_f32_16x16x32_fp8_fp8 v[92:95], v[30:31], v[188:189], v[92:95]
	v_mfma_f32_16x16x32_fp8_fp8 v[96:99], v[34:35], v[188:189], v[96:99]
	v_and_b32_e32 v199, s29, v244
	s_cmp_eq_u32 s50, 1
	v_cmp_ne_u32_e32 vcc, 0, v199
	s_cbranch_scc1 .Lbm3_Bg3_near
	v_add_f32_e32 v200, v81, v193
	v_cndmask_b32_e32 v200, v77, v200, vcc
	v_pk_fma_f32 v[84:85], v[84:85], s[10:11], v[200:201] op_sel_hi:[1,1,0]
	v_pk_fma_f32 v[86:87], v[86:87], s[10:11], v[200:201] op_sel_hi:[1,1,0]
	v_pk_fma_f32 v[88:89], v[88:89], s[10:11], v[200:201] op_sel_hi:[1,1,0]
	v_pk_fma_f32 v[90:91], v[90:91], s[10:11], v[200:201] op_sel_hi:[1,1,0]
	v_pk_fma_f32 v[92:93], v[92:93], s[10:11], v[200:201] op_sel_hi:[1,1,0]
	v_pk_fma_f32 v[94:95], v[94:95], s[10:11], v[200:201] op_sel_hi:[1,1,0]
	v_pk_fma_f32 v[96:97], v[96:97], s[10:11], v[200:201] op_sel_hi:[1,1,0]
	v_pk_fma_f32 v[98:99], v[98:99], s[10:11], v[200:201] op_sel_hi:[1,1,0]
	s_cmp_eq_u32 s35, 0
	s_cbranch_scc1 .Lbm3_Bg3_max
	v_exp_f32_e32 v84, v84
	v_exp_f32_e32 v85, v85
	v_exp_f32_e32 v86, v86
	v_exp_f32_e32 v87, v87
	v_exp_f32_e32 v88, v88
	v_exp_f32_e32 v89, v89
	v_exp_f32_e32 v90, v90
	v_exp_f32_e32 v91, v91
	v_exp_f32_e32 v92, v92
	v_exp_f32_e32 v93, v93
	v_exp_f32_e32 v94, v94
	v_exp_f32_e32 v95, v95
	v_exp_f32_e32 v96, v96
	v_exp_f32_e32 v97, v97
	v_exp_f32_e32 v98, v98
	v_exp_f32_e32 v99, v99
	v_pk_add_f32 v[248:249], v[84:85], v[86:87]
	v_pk_add_f32 v[248:249], v[248:249], v[88:89]
	v_pk_add_f32 v[248:249], v[248:249], v[90:91]
	v_pk_add_f32 v[248:249], v[248:249], v[92:93]
	v_pk_add_f32 v[248:249], v[248:249], v[94:95]
	v_pk_add_f32 v[248:249], v[248:249], v[96:97]
	v_pk_add_f32 v[248:249], v[248:249], v[98:99]
	v_add_f32_e32 v248, v248, v249
	v_cmp_lt_f32_e32 vcc, 0x43800000, v248
	s_cbranch_vccnz .Lbm3_Bg3_redo
	v_cvt_pk_fp8_f32 v84, v84, v85
	v_cvt_pk_fp8_f32 v85, v88, v89
	v_cvt_pk_fp8_f32 v84, v86, v87 op_sel:[0,0,1]
	v_cvt_pk_fp8_f32 v85, v90, v91 op_sel:[0,0,1]
	v_cvt_pk_fp8_f32 v86, v92, v93
	v_cvt_pk_fp8_f32 v87, v96, v97
	v_cvt_pk_fp8_f32 v86, v94, v95 op_sel:[0,0,1]
	v_cvt_pk_fp8_f32 v87, v98, v99 op_sel:[0,0,1]
	v_add_f32_e32 v197, v197, v248
	s_waitcnt vmcnt(8)
	s_nop 1
	v_mfma_f32_16x16x32_fp8_fp8 v[148:151], v[52:53], v[84:85], v[148:151]
	v_mfma_f32_16x16x32_fp8_fp8 v[152:155], v[54:55], v[84:85], v[152:155]
	v_mfma_f32_16x16x32_fp8_fp8 v[156:159], v[56:57], v[84:85], v[156:159]
	v_mfma_f32_16x16x32_fp8_fp8 v[160:163], v[58:59], v[84:85], v[160:163]
	v_mfma_f32_16x16x32_fp8_fp8 v[148:151], v[60:61], v[86:87], v[148:151]
	v_mfma_f32_16x16x32_fp8_fp8 v[152:155], v[62:63], v[86:87], v[152:155]
	v_mfma_f32_16x16x32_fp8_fp8 v[156:159], v[64:65], v[86:87], v[156:159]
	v_mfma_f32_16x16x32_fp8_fp8 v[160:163], v[66:67], v[86:87], v[160:163]
	s_branch .Lbm3_Bg3_skip
.Lbm3_Bg3_redo:
	v_mfma_f32_16x16x32_fp8_fp8 v[84:87], v[20:21], v[186:187], 0
	v_mfma_f32_16x16x32_fp8_fp8 v[88:91], v[24:25], v[186:187], 0
	v_mfma_f32_16x16x32_fp8_fp8 v[92:95], v[28:29], v[186:187], 0
	v_mfma_f32_16x16x32_fp8_fp8 v[96:99], v[32:33], v[186:187], 0
	v_mfma_f32_16x16x32_fp8_fp8 v[84:87], v[22:23], v[188:189], v[84:87]
	v_mfma_f32_16x16x32_fp8_fp8 v[88:91], v[26:27], v[188:189], v[88:91]
	v_mfma_f32_16x16x32_fp8_fp8 v[92:95], v[30:31], v[188:189], v[92:95]
	v_mfma_f32_16x16x32_fp8_fp8 v[96:99], v[34:35], v[188:189], v[96:99]
	s_nop 7
	v_pk_fma_f32 v[84:85], v[84:85], s[10:11], v[200:201] op_sel_hi:[1,1,0]
	v_pk_fma_f32 v[86:87], v[86:87], s[10:11], v[200:201] op_sel_hi:[1,1,0]
	v_pk_fma_f32 v[88:89], v[88:89], s[10:11], v[200:201] op_sel_hi:[1,1,0]
	v_pk_fma_f32 v[90:91], v[90:91], s[10:11], v[200:201] op_sel_hi:[1,1,0]
	v_pk_fma_f32 v[92:93], v[92:93], s[10:11], v[200:201] op_sel_hi:[1,1,0]
	v_pk_fma_f32 v[94:95], v[94:95], s[10:11], v[200:201] op_sel_hi:[1,1,0]
	v_pk_fma_f32 v[96:97], v[96:97], s[10:11], v[200:201] op_sel_hi:[1,1,0]
	v_pk_fma_f32 v[98:99], v[98:99], s[10:11], v[200:201] op_sel_hi:[1,1,0]
